# v035 + removed redundant post-barrier lgkmcnt(0) and mid-M setprio 0/1 pairs in the 6 GEMM K-loops
# speedup vs baseline: 1.0105x; 1.0017x over previous
.LBB0_173:
	ds_read_b128 v[144:147], v155
	ds_read_b128 v[148:151], v155 offset:1024
	ds_read_b128 v[158:161], v155 offset:2048
	ds_read_b128 v[162:165], v155 offset:3072
	ds_read_b128 v[166:169], v156
	ds_read_b128 v[170:173], v156 offset:1024
	ds_read_b128 v[174:177], v156 offset:2048
	ds_read_b128 v[178:181], v156 offset:3072
	s_add_u32 s68, s66, 0xfff80080
	s_addc_u32 s69, s67, -1
	s_cmp_eq_u32 s77, 28
	s_cselect_b32 s71, s55, s69
	s_cselect_b32 s70, s59, s68
	s_cselect_b32 s69, s57, s76
	s_cselect_b32 s68, s65, s73
	v_lshl_add_u64 v[214:215], s[66:67], 0, v[136:137]
	s_add_i32 m0, s25, 0xc000
	ds_read_b128 v[182:185], v157
	ds_read_b128 v[186:189], v157 offset:1024
	ds_read_b128 v[190:193], v157 offset:2048
	ds_read_b128 v[194:197], v157 offset:3072
	ds_read_b128 v[198:201], v157 offset:4096
	ds_read_b128 v[202:205], v157 offset:5120
	ds_read_b128 v[206:209], v157 offset:6144
	ds_read_b128 v[210:213], v157 offset:7168
	global_load_lds_dwordx4 v[214:215], off
	v_lshl_add_u64 v[214:215], s[66:67], 0, v[138:139]
	s_add_i32 m0, s25, 0xe000
	s_nop 0
	global_load_lds_dwordx4 v[214:215], off
	s_waitcnt vmcnt(8)
	s_waitcnt lgkmcnt(0)
	s_barrier
	s_setprio 1
	v_mfma_i32_16x16x64_i8 v[124:127], v[144:147], v[182:185], v[124:127]
	v_mfma_i32_16x16x64_i8 v[116:119], v[158:161], v[182:185], v[116:119]
	v_mfma_i32_16x16x64_i8 v[108:111], v[144:147], v[190:193], v[108:111]
	v_mfma_i32_16x16x64_i8 v[100:103], v[158:161], v[190:193], v[100:103]
	v_mfma_i32_16x16x64_i8 v[92:95], v[144:147], v[198:201], v[92:95]
	v_mfma_i32_16x16x64_i8 v[84:87], v[158:161], v[198:201], v[84:87]
	v_mfma_i32_16x16x64_i8 v[76:79], v[144:147], v[206:209], v[76:79]
	v_mfma_i32_16x16x64_i8 v[68:71], v[158:161], v[206:209], v[68:71]
	v_mfma_i32_16x16x64_i8 v[124:127], v[148:151], v[186:189], v[124:127]
	v_mfma_i32_16x16x64_i8 v[116:119], v[162:165], v[186:189], v[116:119]
	v_mfma_i32_16x16x64_i8 v[108:111], v[148:151], v[194:197], v[108:111]
	v_mfma_i32_16x16x64_i8 v[100:103], v[162:165], v[194:197], v[100:103]
	v_mfma_i32_16x16x64_i8 v[92:95], v[148:151], v[202:205], v[92:95]
	v_mfma_i32_16x16x64_i8 v[84:87], v[162:165], v[202:205], v[84:87]
	v_mfma_i32_16x16x64_i8 v[76:79], v[148:151], v[210:213], v[76:79]
	v_mfma_i32_16x16x64_i8 v[68:71], v[162:165], v[210:213], v[68:71]
	v_mfma_i32_16x16x64_i8 v[120:123], v[166:169], v[182:185], v[120:123]
	v_mfma_i32_16x16x64_i8 v[112:115], v[174:177], v[182:185], v[112:115]
	v_mfma_i32_16x16x64_i8 v[104:107], v[166:169], v[190:193], v[104:107]
	v_mfma_i32_16x16x64_i8 v[96:99], v[174:177], v[190:193], v[96:99]
	v_mfma_i32_16x16x64_i8 v[88:91], v[166:169], v[198:201], v[88:91]
	v_mfma_i32_16x16x64_i8 v[80:83], v[174:177], v[198:201], v[80:83]
	v_mfma_i32_16x16x64_i8 v[72:75], v[166:169], v[206:209], v[72:75]
	v_mfma_i32_16x16x64_i8 v[64:67], v[174:177], v[206:209], v[64:67]
	v_mfma_i32_16x16x64_i8 v[120:123], v[170:173], v[186:189], v[120:123]
	v_mfma_i32_16x16x64_i8 v[112:115], v[178:181], v[186:189], v[112:115]
	v_mfma_i32_16x16x64_i8 v[104:107], v[170:173], v[194:197], v[104:107]
	v_mfma_i32_16x16x64_i8 v[96:99], v[178:181], v[194:197], v[96:99]
	v_mfma_i32_16x16x64_i8 v[88:91], v[170:173], v[202:205], v[88:91]
	v_mfma_i32_16x16x64_i8 v[80:83], v[178:181], v[202:205], v[80:83]
	v_mfma_i32_16x16x64_i8 v[72:75], v[170:173], v[210:213], v[72:75]
	v_mfma_i32_16x16x64_i8 v[64:67], v[178:181], v[210:213], v[64:67]
	s_setprio 0
	s_barrier
	s_add_i32 s78, s35, s13
	v_lshl_add_u64 v[214:215], s[68:69], 0, v[132:133]
	s_mov_b32 m0, s78
	ds_read_b128 v[182:185], v157 offset:16384
	ds_read_b128 v[186:189], v157 offset:17408
	ds_read_b128 v[190:193], v157 offset:18432
	ds_read_b128 v[194:197], v157 offset:19456
	ds_read_b128 v[198:201], v157 offset:20480
	ds_read_b128 v[202:205], v157 offset:21504
	ds_read_b128 v[206:209], v157 offset:22528
	ds_read_b128 v[210:213], v157 offset:23552
	global_load_lds_dwordx4 v[214:215], off
	s_add_i32 m0, s78, 0x2000
	s_add_u32 s78, s68, 0x80000
	v_lshl_add_u64 v[216:217], s[68:69], 0, v[128:129]
	s_addc_u32 s79, s69, 0
	s_add_i32 s81, s52, s13
	global_load_lds_dwordx4 v[216:217], off
	v_lshl_add_u64 v[218:219], s[78:79], 0, v[132:133]
	s_mov_b32 m0, s81
	v_lshl_add_u64 v[220:221], s[70:71], 0, v[130:131]
	global_load_lds_dwordx4 v[218:219], off
	v_lshl_add_u64 v[218:219], s[78:79], 0, v[128:129]
	s_add_i32 m0, s81, 0x2000
	s_nop 0
	global_load_lds_dwordx4 v[218:219], off
	v_lshl_add_u64 v[218:219], s[70:71], 0, v[134:135]
	s_mov_b32 m0, s25
	s_nop 0
	global_load_lds_dwordx4 v[218:219], off
	s_mov_b32 m0, s26
	s_nop 0
	global_load_lds_dwordx4 v[220:221], off
	s_waitcnt vmcnt(8)
	s_waitcnt lgkmcnt(0)
	s_barrier
	s_setprio 1
	v_mfma_i32_16x16x64_i8 v[60:63], v[144:147], v[182:185], v[60:63]
	v_mfma_i32_16x16x64_i8 v[52:55], v[158:161], v[182:185], v[52:55]
	v_mfma_i32_16x16x64_i8 v[44:47], v[144:147], v[190:193], v[44:47]
	v_mfma_i32_16x16x64_i8 v[36:39], v[158:161], v[190:193], v[36:39]
	v_mfma_i32_16x16x64_i8 v[28:31], v[144:147], v[198:201], v[28:31]
	v_mfma_i32_16x16x64_i8 v[20:23], v[158:161], v[198:201], v[20:23]
	v_mfma_i32_16x16x64_i8 v[12:15], v[144:147], v[206:209], v[12:15]
	v_mfma_i32_16x16x64_i8 v[4:7], v[158:161], v[206:209], v[4:7]
	v_mfma_i32_16x16x64_i8 v[60:63], v[148:151], v[186:189], v[60:63]
	v_mfma_i32_16x16x64_i8 v[52:55], v[162:165], v[186:189], v[52:55]
	v_mfma_i32_16x16x64_i8 v[44:47], v[148:151], v[194:197], v[44:47]
	v_mfma_i32_16x16x64_i8 v[36:39], v[162:165], v[194:197], v[36:39]
	v_mfma_i32_16x16x64_i8 v[28:31], v[148:151], v[202:205], v[28:31]
	v_mfma_i32_16x16x64_i8 v[20:23], v[162:165], v[202:205], v[20:23]
	v_mfma_i32_16x16x64_i8 v[12:15], v[148:151], v[210:213], v[12:15]
	v_mfma_i32_16x16x64_i8 v[4:7], v[162:165], v[210:213], v[4:7]
	v_mfma_i32_16x16x64_i8 v[56:59], v[166:169], v[182:185], v[56:59]
	v_mfma_i32_16x16x64_i8 v[48:51], v[174:177], v[182:185], v[48:51]
	v_mfma_i32_16x16x64_i8 v[40:43], v[166:169], v[190:193], v[40:43]
	v_mfma_i32_16x16x64_i8 v[32:35], v[174:177], v[190:193], v[32:35]
	v_mfma_i32_16x16x64_i8 v[24:27], v[166:169], v[198:201], v[24:27]
	v_mfma_i32_16x16x64_i8 v[16:19], v[174:177], v[198:201], v[16:19]
	v_mfma_i32_16x16x64_i8 v[8:11], v[166:169], v[206:209], v[8:11]
	v_mfma_i32_16x16x64_i8 v[0:3], v[174:177], v[206:209], v[0:3]
	v_mfma_i32_16x16x64_i8 v[56:59], v[170:173], v[186:189], v[56:59]
	v_mfma_i32_16x16x64_i8 v[48:51], v[178:181], v[186:189], v[48:51]
	v_mfma_i32_16x16x64_i8 v[40:43], v[170:173], v[194:197], v[40:43]
	v_mfma_i32_16x16x64_i8 v[32:35], v[178:181], v[194:197], v[32:35]
	v_mfma_i32_16x16x64_i8 v[24:27], v[170:173], v[202:205], v[24:27]
	v_mfma_i32_16x16x64_i8 v[16:19], v[178:181], v[202:205], v[16:19]
	v_mfma_i32_16x16x64_i8 v[8:11], v[170:173], v[210:213], v[8:11]
	v_mfma_i32_16x16x64_i8 v[0:3], v[178:181], v[210:213], v[0:3]
	s_setprio 0
	s_barrier
	s_add_i32 s78, 0, 0x18000
	s_add_i32 s79, 0, 0x1c000
	v_add_u32_e32 v162, s78, v153
	v_add_u32_e32 v178, s79, v153
	ds_read_b128 v[144:147], v162
	ds_read_b128 v[148:151], v162 offset:1024
	ds_read_b128 v[158:161], v162 offset:2048
	ds_read_b128 v[162:165], v162 offset:3072
	ds_read_b128 v[166:169], v178
	ds_read_b128 v[170:173], v178 offset:1024
	ds_read_b128 v[174:177], v178 offset:2048
	ds_read_b128 v[178:181], v178 offset:3072
	s_add_u32 s70, s70, 0x80000
	s_addc_u32 s71, s71, 0
	s_mov_b32 m0, s27
	v_lshl_add_u64 v[222:223], s[70:71], 0, v[134:135]
	ds_read_b128 v[182:185], v157 offset:32768
	ds_read_b128 v[186:189], v157 offset:33792
	ds_read_b128 v[190:193], v157 offset:34816
	ds_read_b128 v[194:197], v157 offset:35840
	ds_read_b128 v[198:201], v157 offset:36864
	ds_read_b128 v[202:205], v157 offset:37888
	ds_read_b128 v[206:209], v157 offset:38912
	ds_read_b128 v[210:213], v157 offset:39936
	global_load_lds_dwordx4 v[222:223], off
	v_lshl_add_u64 v[222:223], s[70:71], 0, v[130:131]
	s_mov_b32 m0, s28
	s_nop 0
	global_load_lds_dwordx4 v[222:223], off
	s_waitcnt vmcnt(8)
	s_waitcnt lgkmcnt(0)
	s_barrier
	s_setprio 1
	v_mfma_i32_16x16x64_i8 v[124:127], v[144:147], v[182:185], v[124:127]
	v_mfma_i32_16x16x64_i8 v[116:119], v[158:161], v[182:185], v[116:119]
	v_mfma_i32_16x16x64_i8 v[108:111], v[144:147], v[190:193], v[108:111]
	v_mfma_i32_16x16x64_i8 v[100:103], v[158:161], v[190:193], v[100:103]
	v_mfma_i32_16x16x64_i8 v[92:95], v[144:147], v[198:201], v[92:95]
	v_mfma_i32_16x16x64_i8 v[84:87], v[158:161], v[198:201], v[84:87]
	v_mfma_i32_16x16x64_i8 v[76:79], v[144:147], v[206:209], v[76:79]
	v_mfma_i32_16x16x64_i8 v[68:71], v[158:161], v[206:209], v[68:71]
	v_mfma_i32_16x16x64_i8 v[124:127], v[148:151], v[186:189], v[124:127]
	v_mfma_i32_16x16x64_i8 v[116:119], v[162:165], v[186:189], v[116:119]
	v_mfma_i32_16x16x64_i8 v[108:111], v[148:151], v[194:197], v[108:111]
	v_mfma_i32_16x16x64_i8 v[100:103], v[162:165], v[194:197], v[100:103]
	v_mfma_i32_16x16x64_i8 v[92:95], v[148:151], v[202:205], v[92:95]
	v_mfma_i32_16x16x64_i8 v[84:87], v[162:165], v[202:205], v[84:87]
	v_mfma_i32_16x16x64_i8 v[76:79], v[148:151], v[210:213], v[76:79]
	v_mfma_i32_16x16x64_i8 v[68:71], v[162:165], v[210:213], v[68:71]
	v_mfma_i32_16x16x64_i8 v[120:123], v[166:169], v[182:185], v[120:123]
	v_mfma_i32_16x16x64_i8 v[112:115], v[174:177], v[182:185], v[112:115]
	v_mfma_i32_16x16x64_i8 v[104:107], v[166:169], v[190:193], v[104:107]
	v_mfma_i32_16x16x64_i8 v[96:99], v[174:177], v[190:193], v[96:99]
	v_mfma_i32_16x16x64_i8 v[88:91], v[166:169], v[198:201], v[88:91]
	v_mfma_i32_16x16x64_i8 v[80:83], v[174:177], v[198:201], v[80:83]
	v_mfma_i32_16x16x64_i8 v[72:75], v[166:169], v[206:209], v[72:75]
	v_mfma_i32_16x16x64_i8 v[64:67], v[174:177], v[206:209], v[64:67]
	v_mfma_i32_16x16x64_i8 v[120:123], v[170:173], v[186:189], v[120:123]
	v_mfma_i32_16x16x64_i8 v[112:115], v[178:181], v[186:189], v[112:115]
	v_mfma_i32_16x16x64_i8 v[104:107], v[170:173], v[194:197], v[104:107]
	v_mfma_i32_16x16x64_i8 v[96:99], v[178:181], v[194:197], v[96:99]
	v_mfma_i32_16x16x64_i8 v[88:91], v[170:173], v[202:205], v[88:91]
	v_mfma_i32_16x16x64_i8 v[80:83], v[178:181], v[202:205], v[80:83]
	v_mfma_i32_16x16x64_i8 v[72:75], v[170:173], v[210:213], v[72:75]
	v_mfma_i32_16x16x64_i8 v[64:67], v[178:181], v[210:213], v[64:67]
	s_setprio 0
	s_barrier
	s_add_i32 s70, s78, s13
	v_lshl_add_u64 v[214:215], v[214:215], 0, s[14:15]
	s_mov_b32 m0, s70
	ds_read_b128 v[182:185], v157 offset:49152
	ds_read_b128 v[186:189], v157 offset:50176
	ds_read_b128 v[190:193], v157 offset:51200
	ds_read_b128 v[194:197], v157 offset:52224
	ds_read_b128 v[198:201], v157 offset:53248
	ds_read_b128 v[202:205], v157 offset:54272
	ds_read_b128 v[206:209], v157 offset:55296
	ds_read_b128 v[210:213], v157 offset:56320
	global_load_lds_dwordx4 v[214:215], off
	s_add_i32 m0, s70, 0x2000
	s_add_u32 s68, s68, 0x80080
	v_lshl_add_u64 v[214:215], v[216:217], 0, s[14:15]
	s_addc_u32 s69, s69, 0
	s_add_i32 s70, s79, s13
	global_load_lds_dwordx4 v[214:215], off
	v_lshl_add_u64 v[214:215], s[68:69], 0, v[132:133]
	s_mov_b32 m0, s70
	s_nop 0
	global_load_lds_dwordx4 v[214:215], off
	v_lshl_add_u64 v[214:215], s[68:69], 0, v[128:129]
	s_add_i32 m0, s70, 0x2000
	s_nop 0
	global_load_lds_dwordx4 v[214:215], off
	v_lshl_add_u64 v[214:215], v[218:219], 0, s[14:15]
	s_mov_b32 m0, s31
	s_nop 0
	global_load_lds_dwordx4 v[214:215], off
	v_lshl_add_u64 v[214:215], v[220:221], 0, s[14:15]
	s_mov_b32 m0, s33
	s_nop 0
	global_load_lds_dwordx4 v[214:215], off
	s_waitcnt vmcnt(8)
	s_waitcnt lgkmcnt(0)
	s_barrier
	s_setprio 1
	v_mfma_i32_16x16x64_i8 v[60:63], v[144:147], v[182:185], v[60:63]
	v_mfma_i32_16x16x64_i8 v[52:55], v[158:161], v[182:185], v[52:55]
	v_mfma_i32_16x16x64_i8 v[44:47], v[144:147], v[190:193], v[44:47]
	v_mfma_i32_16x16x64_i8 v[36:39], v[158:161], v[190:193], v[36:39]
	v_mfma_i32_16x16x64_i8 v[28:31], v[144:147], v[198:201], v[28:31]
	v_mfma_i32_16x16x64_i8 v[20:23], v[158:161], v[198:201], v[20:23]
	v_mfma_i32_16x16x64_i8 v[12:15], v[144:147], v[206:209], v[12:15]
	v_mfma_i32_16x16x64_i8 v[4:7], v[158:161], v[206:209], v[4:7]
	v_mfma_i32_16x16x64_i8 v[60:63], v[148:151], v[186:189], v[60:63]
	v_mfma_i32_16x16x64_i8 v[52:55], v[162:165], v[186:189], v[52:55]
	v_mfma_i32_16x16x64_i8 v[44:47], v[148:151], v[194:197], v[44:47]
	v_mfma_i32_16x16x64_i8 v[36:39], v[162:165], v[194:197], v[36:39]
	v_mfma_i32_16x16x64_i8 v[28:31], v[148:151], v[202:205], v[28:31]
	v_mfma_i32_16x16x64_i8 v[20:23], v[162:165], v[202:205], v[20:23]
	v_mfma_i32_16x16x64_i8 v[12:15], v[148:151], v[210:213], v[12:15]
	v_mfma_i32_16x16x64_i8 v[4:7], v[162:165], v[210:213], v[4:7]
	v_mfma_i32_16x16x64_i8 v[56:59], v[166:169], v[182:185], v[56:59]
	v_mfma_i32_16x16x64_i8 v[48:51], v[174:177], v[182:185], v[48:51]
	v_mfma_i32_16x16x64_i8 v[40:43], v[166:169], v[190:193], v[40:43]
	v_mfma_i32_16x16x64_i8 v[32:35], v[174:177], v[190:193], v[32:35]
	v_mfma_i32_16x16x64_i8 v[24:27], v[166:169], v[198:201], v[24:27]
	v_mfma_i32_16x16x64_i8 v[16:19], v[174:177], v[198:201], v[16:19]
	v_mfma_i32_16x16x64_i8 v[8:11], v[166:169], v[206:209], v[8:11]
	v_mfma_i32_16x16x64_i8 v[0:3], v[174:177], v[206:209], v[0:3]
	v_mfma_i32_16x16x64_i8 v[56:59], v[170:173], v[186:189], v[56:59]
	v_mfma_i32_16x16x64_i8 v[48:51], v[178:181], v[186:189], v[48:51]
	v_mfma_i32_16x16x64_i8 v[40:43], v[170:173], v[194:197], v[40:43]
	v_mfma_i32_16x16x64_i8 v[32:35], v[178:181], v[194:197], v[32:35]
	v_mfma_i32_16x16x64_i8 v[24:27], v[170:173], v[202:205], v[24:27]
	v_mfma_i32_16x16x64_i8 v[16:19], v[178:181], v[202:205], v[16:19]
	v_mfma_i32_16x16x64_i8 v[8:11], v[170:173], v[210:213], v[8:11]
	v_mfma_i32_16x16x64_i8 v[0:3], v[178:181], v[210:213], v[0:3]
	s_setprio 0
	s_barrier
	s_add_i32 s77, s77, 2
	s_add_u32 s66, s66, 0x100
	s_addc_u32 s67, s67, 0
	s_add_u32 s73, s73, 0x100
	s_addc_u32 s76, s76, 0
	s_cmp_gt_u32 s77, 29
	s_cbranch_scc0 .LBB0_173
	s_and_b64 vcc, exec, s[20:21]
	s_cbranch_vccz .LBB0_176
	s_barrier

.LBB0_258:
	ds_read_b128 v[152:155], v149
	ds_read_b128 v[156:159], v149 offset:1024
	ds_read_b128 v[160:163], v149 offset:2048
	ds_read_b128 v[164:167], v149 offset:3072
	ds_read_b128 v[168:171], v150
	ds_read_b128 v[172:175], v150 offset:1024
	ds_read_b128 v[176:179], v150 offset:2048
	ds_read_b128 v[180:183], v150 offset:3072
	s_add_u32 s36, s22, 0x100
	s_addc_u32 s37, s23, 0
	s_cmpk_eq_i32 s62, 0xa8
	s_cselect_b32 s57, s5, s37
	s_cselect_b32 s56, s4, s36
	s_cselect_b32 s41, s21, s61
	s_cselect_b32 s40, s20, s60
	v_lshl_add_u64 v[144:145], s[22:23], 0, v[136:137]
	s_add_i32 m0, s25, 0xc000
	ds_read_b128 v[184:187], v151
	ds_read_b128 v[188:191], v151 offset:1024
	ds_read_b128 v[192:195], v151 offset:2048
	ds_read_b128 v[196:199], v151 offset:3072
	ds_read_b128 v[200:203], v151 offset:4096
	ds_read_b128 v[204:207], v151 offset:5120
	ds_read_b128 v[208:211], v151 offset:6144
	ds_read_b128 v[212:215], v151 offset:7168
	global_load_lds_dwordx4 v[144:145], off
	v_lshl_add_u64 v[144:145], s[22:23], 0, v[138:139]
	s_add_i32 m0, s25, 0xe000
	s_nop 0
	global_load_lds_dwordx4 v[144:145], off
	s_waitcnt vmcnt(8)
	s_waitcnt lgkmcnt(0)
	s_barrier
	s_setprio 1
	v_mfma_f32_16x16x32_bf16 v[124:127], v[152:155], v[184:187], v[124:127]
	v_mfma_f32_16x16x32_bf16 v[120:123], v[160:163], v[184:187], v[120:123]
	v_mfma_f32_16x16x32_bf16 v[116:119], v[152:155], v[192:195], v[116:119]
	v_mfma_f32_16x16x32_bf16 v[108:111], v[160:163], v[192:195], v[108:111]
	v_mfma_f32_16x16x32_bf16 v[100:103], v[152:155], v[200:203], v[100:103]
	v_mfma_f32_16x16x32_bf16 v[92:95], v[160:163], v[200:203], v[92:95]
	v_mfma_f32_16x16x32_bf16 v[84:87], v[152:155], v[208:211], v[84:87]
	v_mfma_f32_16x16x32_bf16 v[76:79], v[160:163], v[208:211], v[76:79]
	v_mfma_f32_16x16x32_bf16 v[124:127], v[156:159], v[188:191], v[124:127]
	v_mfma_f32_16x16x32_bf16 v[120:123], v[164:167], v[188:191], v[120:123]
	v_mfma_f32_16x16x32_bf16 v[116:119], v[156:159], v[196:199], v[116:119]
	v_mfma_f32_16x16x32_bf16 v[108:111], v[164:167], v[196:199], v[108:111]
	v_mfma_f32_16x16x32_bf16 v[100:103], v[156:159], v[204:207], v[100:103]
	v_mfma_f32_16x16x32_bf16 v[92:95], v[164:167], v[204:207], v[92:95]
	v_mfma_f32_16x16x32_bf16 v[84:87], v[156:159], v[212:215], v[84:87]
	v_mfma_f32_16x16x32_bf16 v[76:79], v[164:167], v[212:215], v[76:79]
	v_mfma_f32_16x16x32_bf16 v[112:115], v[168:171], v[184:187], v[112:115]
	v_mfma_f32_16x16x32_bf16 v[104:107], v[176:179], v[184:187], v[104:107]
	v_mfma_f32_16x16x32_bf16 v[96:99], v[168:171], v[192:195], v[96:99]
	v_mfma_f32_16x16x32_bf16 v[88:91], v[176:179], v[192:195], v[88:91]
	v_mfma_f32_16x16x32_bf16 v[80:83], v[168:171], v[200:203], v[80:83]
	v_mfma_f32_16x16x32_bf16 v[72:75], v[176:179], v[200:203], v[72:75]
	v_mfma_f32_16x16x32_bf16 v[68:71], v[168:171], v[208:211], v[68:71]
	v_mfma_f32_16x16x32_bf16 v[64:67], v[176:179], v[208:211], v[64:67]
	v_mfma_f32_16x16x32_bf16 v[112:115], v[172:175], v[188:191], v[112:115]
	v_mfma_f32_16x16x32_bf16 v[104:107], v[180:183], v[188:191], v[104:107]
	v_mfma_f32_16x16x32_bf16 v[96:99], v[172:175], v[196:199], v[96:99]
	v_mfma_f32_16x16x32_bf16 v[88:91], v[180:183], v[196:199], v[88:91]
	v_mfma_f32_16x16x32_bf16 v[80:83], v[172:175], v[204:207], v[80:83]
	v_mfma_f32_16x16x32_bf16 v[72:75], v[180:183], v[204:207], v[72:75]
	v_mfma_f32_16x16x32_bf16 v[68:71], v[172:175], v[212:215], v[68:71]
	v_mfma_f32_16x16x32_bf16 v[64:67], v[180:183], v[212:215], v[64:67]
	s_setprio 0
	s_barrier
	s_add_i32 s22, s35, s3
	v_lshl_add_u64 v[144:145], s[40:41], 0, v[132:133]
	s_mov_b32 m0, s22
	ds_read_b128 v[184:187], v151 offset:16384
	ds_read_b128 v[188:191], v151 offset:17408
	ds_read_b128 v[192:195], v151 offset:18432
	ds_read_b128 v[196:199], v151 offset:19456
	ds_read_b128 v[200:203], v151 offset:20480
	ds_read_b128 v[204:207], v151 offset:21504
	ds_read_b128 v[208:211], v151 offset:22528
	ds_read_b128 v[212:215], v151 offset:23552
	global_load_lds_dwordx4 v[144:145], off
	s_add_i32 m0, s22, 0x2000
	s_add_u32 s22, s40, 0x2b0000
	v_lshl_add_u64 v[216:217], s[40:41], 0, v[128:129]
	s_addc_u32 s23, s41, 0
	s_add_i32 s63, s52, s3
	global_load_lds_dwordx4 v[216:217], off
	v_lshl_add_u64 v[218:219], s[22:23], 0, v[132:133]
	s_mov_b32 m0, s63
	v_lshl_add_u64 v[220:221], s[56:57], 0, v[130:131]
	global_load_lds_dwordx4 v[218:219], off
	v_lshl_add_u64 v[218:219], s[22:23], 0, v[128:129]
	s_add_i32 m0, s63, 0x2000
	s_nop 0
	global_load_lds_dwordx4 v[218:219], off
	v_lshl_add_u64 v[218:219], s[56:57], 0, v[134:135]
	s_mov_b32 m0, s25
	s_nop 0
	global_load_lds_dwordx4 v[218:219], off
	s_mov_b32 m0, s26
	s_nop 0
	global_load_lds_dwordx4 v[220:221], off
	s_waitcnt vmcnt(8)
	s_waitcnt lgkmcnt(0)
	s_barrier
	s_setprio 1
	v_mfma_f32_16x16x32_bf16 v[60:63], v[152:155], v[184:187], v[60:63]
	v_mfma_f32_16x16x32_bf16 v[56:59], v[160:163], v[184:187], v[56:59]
	v_mfma_f32_16x16x32_bf16 v[52:55], v[152:155], v[192:195], v[52:55]
	v_mfma_f32_16x16x32_bf16 v[44:47], v[160:163], v[192:195], v[44:47]
	v_mfma_f32_16x16x32_bf16 v[36:39], v[152:155], v[200:203], v[36:39]
	v_mfma_f32_16x16x32_bf16 v[28:31], v[160:163], v[200:203], v[28:31]
	v_mfma_f32_16x16x32_bf16 v[20:23], v[152:155], v[208:211], v[20:23]
	v_mfma_f32_16x16x32_bf16 v[12:15], v[160:163], v[208:211], v[12:15]
	v_mfma_f32_16x16x32_bf16 v[60:63], v[156:159], v[188:191], v[60:63]
	v_mfma_f32_16x16x32_bf16 v[56:59], v[164:167], v[188:191], v[56:59]
	v_mfma_f32_16x16x32_bf16 v[52:55], v[156:159], v[196:199], v[52:55]
	v_mfma_f32_16x16x32_bf16 v[44:47], v[164:167], v[196:199], v[44:47]
	v_mfma_f32_16x16x32_bf16 v[36:39], v[156:159], v[204:207], v[36:39]
	v_mfma_f32_16x16x32_bf16 v[28:31], v[164:167], v[204:207], v[28:31]
	v_mfma_f32_16x16x32_bf16 v[20:23], v[156:159], v[212:215], v[20:23]
	v_mfma_f32_16x16x32_bf16 v[12:15], v[164:167], v[212:215], v[12:15]
	v_mfma_f32_16x16x32_bf16 v[48:51], v[168:171], v[184:187], v[48:51]
	v_mfma_f32_16x16x32_bf16 v[40:43], v[176:179], v[184:187], v[40:43]
	v_mfma_f32_16x16x32_bf16 v[32:35], v[168:171], v[192:195], v[32:35]
	v_mfma_f32_16x16x32_bf16 v[24:27], v[176:179], v[192:195], v[24:27]
	v_mfma_f32_16x16x32_bf16 v[16:19], v[168:171], v[200:203], v[16:19]
	v_mfma_f32_16x16x32_bf16 v[8:11], v[176:179], v[200:203], v[8:11]
	v_mfma_f32_16x16x32_bf16 v[4:7], v[168:171], v[208:211], v[4:7]
	v_mfma_f32_16x16x32_bf16 v[0:3], v[176:179], v[208:211], v[0:3]
	v_mfma_f32_16x16x32_bf16 v[48:51], v[172:175], v[188:191], v[48:51]
	v_mfma_f32_16x16x32_bf16 v[40:43], v[180:183], v[188:191], v[40:43]
	v_mfma_f32_16x16x32_bf16 v[32:35], v[172:175], v[196:199], v[32:35]
	v_mfma_f32_16x16x32_bf16 v[24:27], v[180:183], v[196:199], v[24:27]
	v_mfma_f32_16x16x32_bf16 v[16:19], v[172:175], v[204:207], v[16:19]
	v_mfma_f32_16x16x32_bf16 v[8:11], v[180:183], v[204:207], v[8:11]
	v_mfma_f32_16x16x32_bf16 v[4:7], v[172:175], v[212:215], v[4:7]
	v_mfma_f32_16x16x32_bf16 v[0:3], v[180:183], v[212:215], v[0:3]
	s_setprio 0
	s_barrier
	s_add_i32 s63, 0, 0x18000
	s_add_i32 s64, 0, 0x1c000
	v_add_u32_e32 v164, s63, v147
	v_add_u32_e32 v180, s64, v147
	ds_read_b128 v[152:155], v164
	ds_read_b128 v[156:159], v164 offset:1024
	ds_read_b128 v[160:163], v164 offset:2048
	ds_read_b128 v[164:167], v164 offset:3072
	ds_read_b128 v[168:171], v180
	ds_read_b128 v[172:175], v180 offset:1024
	ds_read_b128 v[176:179], v180 offset:2048
	ds_read_b128 v[180:183], v180 offset:3072
	s_add_u32 s22, s56, 0x2b0000
	s_addc_u32 s23, s57, 0
	s_mov_b32 m0, s27
	v_lshl_add_u64 v[222:223], s[22:23], 0, v[134:135]
	ds_read_b128 v[184:187], v151 offset:32768
	ds_read_b128 v[188:191], v151 offset:33792
	ds_read_b128 v[192:195], v151 offset:34816
	ds_read_b128 v[196:199], v151 offset:35840
	ds_read_b128 v[200:203], v151 offset:36864
	ds_read_b128 v[204:207], v151 offset:37888
	ds_read_b128 v[208:211], v151 offset:38912
	ds_read_b128 v[212:215], v151 offset:39936
	global_load_lds_dwordx4 v[222:223], off
	v_lshl_add_u64 v[222:223], s[22:23], 0, v[130:131]
	s_mov_b32 m0, s28
	s_nop 0
	global_load_lds_dwordx4 v[222:223], off
	s_waitcnt vmcnt(8)
	s_waitcnt lgkmcnt(0)
	s_barrier
	s_setprio 1
	v_mfma_f32_16x16x32_bf16 v[124:127], v[152:155], v[184:187], v[124:127]
	v_mfma_f32_16x16x32_bf16 v[120:123], v[160:163], v[184:187], v[120:123]
	v_mfma_f32_16x16x32_bf16 v[116:119], v[152:155], v[192:195], v[116:119]
	v_mfma_f32_16x16x32_bf16 v[108:111], v[160:163], v[192:195], v[108:111]
	v_mfma_f32_16x16x32_bf16 v[100:103], v[152:155], v[200:203], v[100:103]
	v_mfma_f32_16x16x32_bf16 v[92:95], v[160:163], v[200:203], v[92:95]
	v_mfma_f32_16x16x32_bf16 v[84:87], v[152:155], v[208:211], v[84:87]
	v_mfma_f32_16x16x32_bf16 v[76:79], v[160:163], v[208:211], v[76:79]
	v_mfma_f32_16x16x32_bf16 v[124:127], v[156:159], v[188:191], v[124:127]
	v_mfma_f32_16x16x32_bf16 v[120:123], v[164:167], v[188:191], v[120:123]
	v_mfma_f32_16x16x32_bf16 v[116:119], v[156:159], v[196:199], v[116:119]
	v_mfma_f32_16x16x32_bf16 v[108:111], v[164:167], v[196:199], v[108:111]
	v_mfma_f32_16x16x32_bf16 v[100:103], v[156:159], v[204:207], v[100:103]
	v_mfma_f32_16x16x32_bf16 v[92:95], v[164:167], v[204:207], v[92:95]
	v_mfma_f32_16x16x32_bf16 v[84:87], v[156:159], v[212:215], v[84:87]
	v_mfma_f32_16x16x32_bf16 v[76:79], v[164:167], v[212:215], v[76:79]
	v_mfma_f32_16x16x32_bf16 v[112:115], v[168:171], v[184:187], v[112:115]
	v_mfma_f32_16x16x32_bf16 v[104:107], v[176:179], v[184:187], v[104:107]
	v_mfma_f32_16x16x32_bf16 v[96:99], v[168:171], v[192:195], v[96:99]
	v_mfma_f32_16x16x32_bf16 v[88:91], v[176:179], v[192:195], v[88:91]
	v_mfma_f32_16x16x32_bf16 v[80:83], v[168:171], v[200:203], v[80:83]
	v_mfma_f32_16x16x32_bf16 v[72:75], v[176:179], v[200:203], v[72:75]
	v_mfma_f32_16x16x32_bf16 v[68:71], v[168:171], v[208:211], v[68:71]
	v_mfma_f32_16x16x32_bf16 v[64:67], v[176:179], v[208:211], v[64:67]
	v_mfma_f32_16x16x32_bf16 v[112:115], v[172:175], v[188:191], v[112:115]
	v_mfma_f32_16x16x32_bf16 v[104:107], v[180:183], v[188:191], v[104:107]
	v_mfma_f32_16x16x32_bf16 v[96:99], v[172:175], v[196:199], v[96:99]
	v_mfma_f32_16x16x32_bf16 v[88:91], v[180:183], v[196:199], v[88:91]
	v_mfma_f32_16x16x32_bf16 v[80:83], v[172:175], v[204:207], v[80:83]
	v_mfma_f32_16x16x32_bf16 v[72:75], v[180:183], v[204:207], v[72:75]
	v_mfma_f32_16x16x32_bf16 v[68:71], v[172:175], v[212:215], v[68:71]
	v_mfma_f32_16x16x32_bf16 v[64:67], v[180:183], v[212:215], v[64:67]
	s_setprio 0
	s_barrier
	s_add_i32 s22, s63, s3
	v_lshl_add_u64 v[144:145], v[144:145], 0, s[12:13]
	s_mov_b32 m0, s22
	ds_read_b128 v[184:187], v151 offset:49152
	ds_read_b128 v[188:191], v151 offset:50176
	ds_read_b128 v[192:195], v151 offset:51200
	ds_read_b128 v[196:199], v151 offset:52224
	ds_read_b128 v[200:203], v151 offset:53248
	ds_read_b128 v[204:207], v151 offset:54272
	ds_read_b128 v[208:211], v151 offset:55296
	ds_read_b128 v[212:215], v151 offset:56320
	global_load_lds_dwordx4 v[144:145], off
	s_add_i32 m0, s22, 0x2000
	s_add_u32 s22, s40, 0x2b0080
	v_lshl_add_u64 v[144:145], v[216:217], 0, s[12:13]
	s_addc_u32 s23, s41, 0
	s_add_i32 s40, s64, s3
	global_load_lds_dwordx4 v[144:145], off
	v_lshl_add_u64 v[144:145], s[22:23], 0, v[132:133]
	s_mov_b32 m0, s40
	s_nop 0
	global_load_lds_dwordx4 v[144:145], off
	v_lshl_add_u64 v[144:145], s[22:23], 0, v[128:129]
	s_add_i32 m0, s40, 0x2000
	s_nop 0
	global_load_lds_dwordx4 v[144:145], off
	v_lshl_add_u64 v[144:145], v[218:219], 0, s[12:13]
	s_mov_b32 m0, s31
	s_nop 0
	global_load_lds_dwordx4 v[144:145], off
	v_lshl_add_u64 v[144:145], v[220:221], 0, s[12:13]
	s_mov_b32 m0, s33
	s_nop 0
	global_load_lds_dwordx4 v[144:145], off
	s_waitcnt vmcnt(8)
	s_waitcnt lgkmcnt(0)
	s_barrier
	s_setprio 1
	v_mfma_f32_16x16x32_bf16 v[60:63], v[152:155], v[184:187], v[60:63]
	v_mfma_f32_16x16x32_bf16 v[56:59], v[160:163], v[184:187], v[56:59]
	v_mfma_f32_16x16x32_bf16 v[52:55], v[152:155], v[192:195], v[52:55]
	v_mfma_f32_16x16x32_bf16 v[44:47], v[160:163], v[192:195], v[44:47]
	v_mfma_f32_16x16x32_bf16 v[36:39], v[152:155], v[200:203], v[36:39]
	v_mfma_f32_16x16x32_bf16 v[28:31], v[160:163], v[200:203], v[28:31]
	v_mfma_f32_16x16x32_bf16 v[20:23], v[152:155], v[208:211], v[20:23]
	v_mfma_f32_16x16x32_bf16 v[12:15], v[160:163], v[208:211], v[12:15]
	v_mfma_f32_16x16x32_bf16 v[60:63], v[156:159], v[188:191], v[60:63]
	v_mfma_f32_16x16x32_bf16 v[56:59], v[164:167], v[188:191], v[56:59]
	v_mfma_f32_16x16x32_bf16 v[52:55], v[156:159], v[196:199], v[52:55]
	v_mfma_f32_16x16x32_bf16 v[44:47], v[164:167], v[196:199], v[44:47]
	v_mfma_f32_16x16x32_bf16 v[36:39], v[156:159], v[204:207], v[36:39]
	v_mfma_f32_16x16x32_bf16 v[28:31], v[164:167], v[204:207], v[28:31]
	v_mfma_f32_16x16x32_bf16 v[20:23], v[156:159], v[212:215], v[20:23]
	v_mfma_f32_16x16x32_bf16 v[12:15], v[164:167], v[212:215], v[12:15]
	v_mfma_f32_16x16x32_bf16 v[48:51], v[168:171], v[184:187], v[48:51]
	v_mfma_f32_16x16x32_bf16 v[40:43], v[176:179], v[184:187], v[40:43]
	v_mfma_f32_16x16x32_bf16 v[32:35], v[168:171], v[192:195], v[32:35]
	v_mfma_f32_16x16x32_bf16 v[24:27], v[176:179], v[192:195], v[24:27]
	v_mfma_f32_16x16x32_bf16 v[16:19], v[168:171], v[200:203], v[16:19]
	v_mfma_f32_16x16x32_bf16 v[8:11], v[176:179], v[200:203], v[8:11]
	v_mfma_f32_16x16x32_bf16 v[4:7], v[168:171], v[208:211], v[4:7]
	v_mfma_f32_16x16x32_bf16 v[0:3], v[176:179], v[208:211], v[0:3]
	v_mfma_f32_16x16x32_bf16 v[48:51], v[172:175], v[188:191], v[48:51]
	v_mfma_f32_16x16x32_bf16 v[40:43], v[180:183], v[188:191], v[40:43]
	v_mfma_f32_16x16x32_bf16 v[32:35], v[172:175], v[196:199], v[32:35]
	v_mfma_f32_16x16x32_bf16 v[24:27], v[180:183], v[196:199], v[24:27]
	v_mfma_f32_16x16x32_bf16 v[16:19], v[172:175], v[204:207], v[16:19]
	v_mfma_f32_16x16x32_bf16 v[8:11], v[180:183], v[204:207], v[8:11]
	v_mfma_f32_16x16x32_bf16 v[4:7], v[172:175], v[212:215], v[4:7]
	v_mfma_f32_16x16x32_bf16 v[0:3], v[180:183], v[212:215], v[0:3]
	s_setprio 0
	s_barrier
	s_add_i32 s62, s62, 2
	s_add_u32 s60, s60, 0x100
	s_addc_u32 s61, s61, 0
	s_cmpk_gt_u32 s62, 0xa9
	s_mov_b64 s[22:23], s[36:37]
	s_cbranch_scc0 .LBB0_258
	s_and_b64 vcc, exec, s[14:15]
	s_cbranch_vccz .LBB0_261
	s_barrier

.LBB0_394:
	ds_read_b128 v[156:159], v152
	ds_read_b128 v[160:163], v152 offset:1024
	ds_read_b128 v[164:167], v152 offset:2048
	ds_read_b128 v[168:171], v152 offset:3072
	ds_read_b128 v[172:175], v153
	ds_read_b128 v[176:179], v153 offset:1024
	ds_read_b128 v[180:183], v153 offset:2048
	ds_read_b128 v[184:187], v153 offset:3072
	s_add_u32 s40, s38, 0xfff00080
	s_addc_u32 s41, s39, -1
	s_cmp_eq_u32 s64, 60
	s_cselect_b32 s57, s21, s41
	s_cselect_b32 s56, s60, s40
	s_cselect_b32 s41, s15, s63
	s_cselect_b32 s40, s61, s62
	v_lshl_add_u64 v[148:149], s[38:39], 0, v[140:141]
	s_add_i32 m0, s29, 0xc000
	ds_read_b128 v[188:191], v154
	ds_read_b128 v[192:195], v154 offset:1024
	ds_read_b128 v[196:199], v154 offset:2048
	ds_read_b128 v[200:203], v154 offset:3072
	ds_read_b128 v[204:207], v154 offset:4096
	ds_read_b128 v[208:211], v154 offset:5120
	ds_read_b128 v[212:215], v154 offset:6144
	ds_read_b128 v[216:219], v154 offset:7168
	global_load_lds_dwordx4 v[148:149], off
	v_lshl_add_u64 v[148:149], s[38:39], 0, v[142:143]
	s_add_i32 m0, s29, 0xe000
	s_nop 0
	global_load_lds_dwordx4 v[148:149], off
	s_waitcnt vmcnt(8)
	s_waitcnt lgkmcnt(0)
	s_barrier
	s_setprio 1
	v_mfma_f32_16x16x32_bf16 v[124:127], v[156:159], v[188:191], v[124:127]
	v_mfma_f32_16x16x32_bf16 v[120:123], v[164:167], v[188:191], v[120:123]
	v_mfma_f32_16x16x32_bf16 v[112:115], v[156:159], v[196:199], v[112:115]
	v_mfma_f32_16x16x32_bf16 v[104:107], v[164:167], v[196:199], v[104:107]
	v_mfma_f32_16x16x32_bf16 v[96:99], v[156:159], v[204:207], v[96:99]
	v_mfma_f32_16x16x32_bf16 v[88:91], v[164:167], v[204:207], v[88:91]
	v_mfma_f32_16x16x32_bf16 v[80:83], v[156:159], v[212:215], v[80:83]
	v_mfma_f32_16x16x32_bf16 v[72:75], v[164:167], v[212:215], v[72:75]
	v_mfma_f32_16x16x32_bf16 v[124:127], v[160:163], v[192:195], v[124:127]
	v_mfma_f32_16x16x32_bf16 v[120:123], v[168:171], v[192:195], v[120:123]
	v_mfma_f32_16x16x32_bf16 v[112:115], v[160:163], v[200:203], v[112:115]
	v_mfma_f32_16x16x32_bf16 v[104:107], v[168:171], v[200:203], v[104:107]
	v_mfma_f32_16x16x32_bf16 v[96:99], v[160:163], v[208:211], v[96:99]
	v_mfma_f32_16x16x32_bf16 v[88:91], v[168:171], v[208:211], v[88:91]
	v_mfma_f32_16x16x32_bf16 v[80:83], v[160:163], v[216:219], v[80:83]
	v_mfma_f32_16x16x32_bf16 v[72:75], v[168:171], v[216:219], v[72:75]
	v_mfma_f32_16x16x32_bf16 v[116:119], v[172:175], v[188:191], v[116:119]
	v_mfma_f32_16x16x32_bf16 v[108:111], v[180:183], v[188:191], v[108:111]
	v_mfma_f32_16x16x32_bf16 v[100:103], v[172:175], v[196:199], v[100:103]
	v_mfma_f32_16x16x32_bf16 v[92:95], v[180:183], v[196:199], v[92:95]
	v_mfma_f32_16x16x32_bf16 v[84:87], v[172:175], v[204:207], v[84:87]
	v_mfma_f32_16x16x32_bf16 v[76:79], v[180:183], v[204:207], v[76:79]
	v_mfma_f32_16x16x32_bf16 v[68:71], v[172:175], v[212:215], v[68:71]
	v_mfma_f32_16x16x32_bf16 v[64:67], v[180:183], v[212:215], v[64:67]
	v_mfma_f32_16x16x32_bf16 v[116:119], v[176:179], v[192:195], v[116:119]
	v_mfma_f32_16x16x32_bf16 v[108:111], v[184:187], v[192:195], v[108:111]
	v_mfma_f32_16x16x32_bf16 v[100:103], v[176:179], v[200:203], v[100:103]
	v_mfma_f32_16x16x32_bf16 v[92:95], v[184:187], v[200:203], v[92:95]
	v_mfma_f32_16x16x32_bf16 v[84:87], v[176:179], v[208:211], v[84:87]
	v_mfma_f32_16x16x32_bf16 v[76:79], v[184:187], v[208:211], v[76:79]
	v_mfma_f32_16x16x32_bf16 v[68:71], v[176:179], v[216:219], v[68:71]
	v_mfma_f32_16x16x32_bf16 v[64:67], v[184:187], v[216:219], v[64:67]
	s_setprio 0
	s_barrier
	s_add_i32 s65, s58, s24
	v_lshl_add_u64 v[148:149], s[40:41], 0, v[132:133]
	s_mov_b32 m0, s65
	ds_read_b128 v[188:191], v154 offset:16384
	ds_read_b128 v[192:195], v154 offset:17408
	ds_read_b128 v[196:199], v154 offset:18432
	ds_read_b128 v[200:203], v154 offset:19456
	ds_read_b128 v[204:207], v154 offset:20480
	ds_read_b128 v[208:211], v154 offset:21504
	ds_read_b128 v[212:215], v154 offset:22528
	ds_read_b128 v[216:219], v154 offset:23552
	global_load_lds_dwordx4 v[148:149], off
	s_add_i32 m0, s65, 0x2000
	s_add_u32 s66, s40, 0x100000
	v_lshl_add_u64 v[220:221], s[40:41], 0, v[128:129]
	s_addc_u32 s67, s41, 0
	s_add_i32 s65, s59, s24
	global_load_lds_dwordx4 v[220:221], off
	v_lshl_add_u64 v[222:223], s[66:67], 0, v[132:133]
	s_mov_b32 m0, s65
	v_lshl_add_u64 v[224:225], s[56:57], 0, v[130:131]
	global_load_lds_dwordx4 v[222:223], off
	v_lshl_add_u64 v[222:223], s[66:67], 0, v[128:129]
	s_add_i32 m0, s65, 0x2000
	s_nop 0
	global_load_lds_dwordx4 v[222:223], off
	v_lshl_add_u64 v[222:223], s[56:57], 0, v[134:135]
	s_mov_b32 m0, s29
	s_nop 0
	global_load_lds_dwordx4 v[222:223], off
	s_mov_b32 m0, s30
	s_nop 0
	global_load_lds_dwordx4 v[224:225], off
	s_waitcnt vmcnt(8)
	s_waitcnt lgkmcnt(0)
	s_barrier
	s_setprio 1
	v_mfma_f32_16x16x32_bf16 v[60:63], v[156:159], v[188:191], v[60:63]
	v_mfma_f32_16x16x32_bf16 v[56:59], v[164:167], v[188:191], v[56:59]
	v_mfma_f32_16x16x32_bf16 v[52:55], v[156:159], v[196:199], v[52:55]
	v_mfma_f32_16x16x32_bf16 v[44:47], v[164:167], v[196:199], v[44:47]
	v_mfma_f32_16x16x32_bf16 v[36:39], v[156:159], v[204:207], v[36:39]
	v_mfma_f32_16x16x32_bf16 v[28:31], v[164:167], v[204:207], v[28:31]
	v_mfma_f32_16x16x32_bf16 v[20:23], v[156:159], v[212:215], v[20:23]
	v_mfma_f32_16x16x32_bf16 v[12:15], v[164:167], v[212:215], v[12:15]
	v_mfma_f32_16x16x32_bf16 v[60:63], v[160:163], v[192:195], v[60:63]
	v_mfma_f32_16x16x32_bf16 v[56:59], v[168:171], v[192:195], v[56:59]
	v_mfma_f32_16x16x32_bf16 v[52:55], v[160:163], v[200:203], v[52:55]
	v_mfma_f32_16x16x32_bf16 v[44:47], v[168:171], v[200:203], v[44:47]
	v_mfma_f32_16x16x32_bf16 v[36:39], v[160:163], v[208:211], v[36:39]
	v_mfma_f32_16x16x32_bf16 v[28:31], v[168:171], v[208:211], v[28:31]
	v_mfma_f32_16x16x32_bf16 v[20:23], v[160:163], v[216:219], v[20:23]
	v_mfma_f32_16x16x32_bf16 v[12:15], v[168:171], v[216:219], v[12:15]
	v_mfma_f32_16x16x32_bf16 v[48:51], v[172:175], v[188:191], v[48:51]
	v_mfma_f32_16x16x32_bf16 v[40:43], v[180:183], v[188:191], v[40:43]
	v_mfma_f32_16x16x32_bf16 v[32:35], v[172:175], v[196:199], v[32:35]
	v_mfma_f32_16x16x32_bf16 v[24:27], v[180:183], v[196:199], v[24:27]
	v_mfma_f32_16x16x32_bf16 v[16:19], v[172:175], v[204:207], v[16:19]
	v_mfma_f32_16x16x32_bf16 v[8:11], v[180:183], v[204:207], v[8:11]
	v_mfma_f32_16x16x32_bf16 v[4:7], v[172:175], v[212:215], v[4:7]
	v_mfma_f32_16x16x32_bf16 v[0:3], v[180:183], v[212:215], v[0:3]
	v_mfma_f32_16x16x32_bf16 v[48:51], v[176:179], v[192:195], v[48:51]
	v_mfma_f32_16x16x32_bf16 v[40:43], v[184:187], v[192:195], v[40:43]
	v_mfma_f32_16x16x32_bf16 v[32:35], v[176:179], v[200:203], v[32:35]
	v_mfma_f32_16x16x32_bf16 v[24:27], v[184:187], v[200:203], v[24:27]
	v_mfma_f32_16x16x32_bf16 v[16:19], v[176:179], v[208:211], v[16:19]
	v_mfma_f32_16x16x32_bf16 v[8:11], v[184:187], v[208:211], v[8:11]
	v_mfma_f32_16x16x32_bf16 v[4:7], v[176:179], v[216:219], v[4:7]
	v_mfma_f32_16x16x32_bf16 v[0:3], v[184:187], v[216:219], v[0:3]
	s_setprio 0
	s_barrier
	s_add_i32 s65, 0, 0x18000
	v_add_u32_e32 v155, s65, v151
	s_add_i32 s66, 0, 0x1c000
	ds_read_b128 v[156:159], v155
	ds_read_b128 v[160:163], v155 offset:1024
	ds_read_b128 v[164:167], v155 offset:2048
	ds_read_b128 v[168:171], v155 offset:3072
	v_add_u32_e32 v155, s66, v151
	ds_read_b128 v[172:175], v155
	ds_read_b128 v[176:179], v155 offset:1024
	ds_read_b128 v[180:183], v155 offset:2048
	ds_read_b128 v[184:187], v155 offset:3072
	s_add_u32 s56, s56, 0x100000
	s_addc_u32 s57, s57, 0
	s_mov_b32 m0, s31
	v_lshl_add_u64 v[226:227], s[56:57], 0, v[134:135]
	ds_read_b128 v[188:191], v154 offset:32768
	ds_read_b128 v[192:195], v154 offset:33792
	ds_read_b128 v[196:199], v154 offset:34816
	ds_read_b128 v[200:203], v154 offset:35840
	ds_read_b128 v[204:207], v154 offset:36864
	ds_read_b128 v[208:211], v154 offset:37888
	ds_read_b128 v[212:215], v154 offset:38912
	ds_read_b128 v[216:219], v154 offset:39936
	global_load_lds_dwordx4 v[226:227], off
	v_lshl_add_u64 v[226:227], s[56:57], 0, v[130:131]
	s_mov_b32 m0, s33
	s_nop 0
	global_load_lds_dwordx4 v[226:227], off
	s_waitcnt vmcnt(8)
	s_waitcnt lgkmcnt(0)
	s_barrier
	s_setprio 1
	v_mfma_f32_16x16x32_bf16 v[124:127], v[156:159], v[188:191], v[124:127]
	v_mfma_f32_16x16x32_bf16 v[120:123], v[164:167], v[188:191], v[120:123]
	v_mfma_f32_16x16x32_bf16 v[112:115], v[156:159], v[196:199], v[112:115]
	v_mfma_f32_16x16x32_bf16 v[104:107], v[164:167], v[196:199], v[104:107]
	v_mfma_f32_16x16x32_bf16 v[96:99], v[156:159], v[204:207], v[96:99]
	v_mfma_f32_16x16x32_bf16 v[88:91], v[164:167], v[204:207], v[88:91]
	v_mfma_f32_16x16x32_bf16 v[80:83], v[156:159], v[212:215], v[80:83]
	v_mfma_f32_16x16x32_bf16 v[72:75], v[164:167], v[212:215], v[72:75]
	v_mfma_f32_16x16x32_bf16 v[124:127], v[160:163], v[192:195], v[124:127]
	v_mfma_f32_16x16x32_bf16 v[120:123], v[168:171], v[192:195], v[120:123]
	v_mfma_f32_16x16x32_bf16 v[112:115], v[160:163], v[200:203], v[112:115]
	v_mfma_f32_16x16x32_bf16 v[104:107], v[168:171], v[200:203], v[104:107]
	v_mfma_f32_16x16x32_bf16 v[96:99], v[160:163], v[208:211], v[96:99]
	v_mfma_f32_16x16x32_bf16 v[88:91], v[168:171], v[208:211], v[88:91]
	v_mfma_f32_16x16x32_bf16 v[80:83], v[160:163], v[216:219], v[80:83]
	v_mfma_f32_16x16x32_bf16 v[72:75], v[168:171], v[216:219], v[72:75]
	v_mfma_f32_16x16x32_bf16 v[116:119], v[172:175], v[188:191], v[116:119]
	v_mfma_f32_16x16x32_bf16 v[108:111], v[180:183], v[188:191], v[108:111]
	v_mfma_f32_16x16x32_bf16 v[100:103], v[172:175], v[196:199], v[100:103]
	v_mfma_f32_16x16x32_bf16 v[92:95], v[180:183], v[196:199], v[92:95]
	v_mfma_f32_16x16x32_bf16 v[84:87], v[172:175], v[204:207], v[84:87]
	v_mfma_f32_16x16x32_bf16 v[76:79], v[180:183], v[204:207], v[76:79]
	v_mfma_f32_16x16x32_bf16 v[68:71], v[172:175], v[212:215], v[68:71]
	v_mfma_f32_16x16x32_bf16 v[64:67], v[180:183], v[212:215], v[64:67]
	v_mfma_f32_16x16x32_bf16 v[116:119], v[176:179], v[192:195], v[116:119]
	v_mfma_f32_16x16x32_bf16 v[108:111], v[184:187], v[192:195], v[108:111]
	v_mfma_f32_16x16x32_bf16 v[100:103], v[176:179], v[200:203], v[100:103]
	v_mfma_f32_16x16x32_bf16 v[92:95], v[184:187], v[200:203], v[92:95]
	v_mfma_f32_16x16x32_bf16 v[84:87], v[176:179], v[208:211], v[84:87]
	v_mfma_f32_16x16x32_bf16 v[76:79], v[184:187], v[208:211], v[76:79]
	v_mfma_f32_16x16x32_bf16 v[68:71], v[176:179], v[216:219], v[68:71]
	v_mfma_f32_16x16x32_bf16 v[64:67], v[184:187], v[216:219], v[64:67]
	s_setprio 0
	s_barrier
	s_add_i32 s56, s65, s24
	v_lshl_add_u64 v[148:149], v[148:149], 0, s[10:11]
	s_mov_b32 m0, s56
	ds_read_b128 v[188:191], v154 offset:49152
	ds_read_b128 v[192:195], v154 offset:50176
	ds_read_b128 v[196:199], v154 offset:51200
	ds_read_b128 v[200:203], v154 offset:52224
	ds_read_b128 v[204:207], v154 offset:53248
	ds_read_b128 v[208:211], v154 offset:54272
	ds_read_b128 v[212:215], v154 offset:55296
	ds_read_b128 v[216:219], v154 offset:56320
	global_load_lds_dwordx4 v[148:149], off
	s_add_i32 m0, s56, 0x2000
	s_add_u32 s40, s40, 0x100080
	v_lshl_add_u64 v[148:149], v[220:221], 0, s[10:11]
	s_addc_u32 s41, s41, 0
	s_add_i32 s56, s66, s24
	global_load_lds_dwordx4 v[148:149], off
	v_lshl_add_u64 v[148:149], s[40:41], 0, v[132:133]
	s_mov_b32 m0, s56
	s_nop 0
	global_load_lds_dwordx4 v[148:149], off
	v_lshl_add_u64 v[148:149], s[40:41], 0, v[128:129]
	s_add_i32 m0, s56, 0x2000
	s_nop 0
	global_load_lds_dwordx4 v[148:149], off
	v_lshl_add_u64 v[148:149], v[222:223], 0, s[10:11]
	s_mov_b32 m0, s54
	s_nop 0
	global_load_lds_dwordx4 v[148:149], off
	v_lshl_add_u64 v[148:149], v[224:225], 0, s[10:11]
	s_mov_b32 m0, s55
	s_nop 0
	global_load_lds_dwordx4 v[148:149], off
	s_waitcnt vmcnt(8)
	s_waitcnt lgkmcnt(0)
	s_barrier
	s_setprio 1
	v_mfma_f32_16x16x32_bf16 v[60:63], v[156:159], v[188:191], v[60:63]
	v_mfma_f32_16x16x32_bf16 v[56:59], v[164:167], v[188:191], v[56:59]
	v_mfma_f32_16x16x32_bf16 v[52:55], v[156:159], v[196:199], v[52:55]
	v_mfma_f32_16x16x32_bf16 v[44:47], v[164:167], v[196:199], v[44:47]
	v_mfma_f32_16x16x32_bf16 v[36:39], v[156:159], v[204:207], v[36:39]
	v_mfma_f32_16x16x32_bf16 v[28:31], v[164:167], v[204:207], v[28:31]
	v_mfma_f32_16x16x32_bf16 v[20:23], v[156:159], v[212:215], v[20:23]
	v_mfma_f32_16x16x32_bf16 v[12:15], v[164:167], v[212:215], v[12:15]
	v_mfma_f32_16x16x32_bf16 v[60:63], v[160:163], v[192:195], v[60:63]
	v_mfma_f32_16x16x32_bf16 v[56:59], v[168:171], v[192:195], v[56:59]
	v_mfma_f32_16x16x32_bf16 v[52:55], v[160:163], v[200:203], v[52:55]
	v_mfma_f32_16x16x32_bf16 v[44:47], v[168:171], v[200:203], v[44:47]
	v_mfma_f32_16x16x32_bf16 v[36:39], v[160:163], v[208:211], v[36:39]
	v_mfma_f32_16x16x32_bf16 v[28:31], v[168:171], v[208:211], v[28:31]
	v_mfma_f32_16x16x32_bf16 v[20:23], v[160:163], v[216:219], v[20:23]
	v_mfma_f32_16x16x32_bf16 v[12:15], v[168:171], v[216:219], v[12:15]
	v_mfma_f32_16x16x32_bf16 v[48:51], v[172:175], v[188:191], v[48:51]
	v_mfma_f32_16x16x32_bf16 v[40:43], v[180:183], v[188:191], v[40:43]
	v_mfma_f32_16x16x32_bf16 v[32:35], v[172:175], v[196:199], v[32:35]
	v_mfma_f32_16x16x32_bf16 v[24:27], v[180:183], v[196:199], v[24:27]
	v_mfma_f32_16x16x32_bf16 v[16:19], v[172:175], v[204:207], v[16:19]
	v_mfma_f32_16x16x32_bf16 v[8:11], v[180:183], v[204:207], v[8:11]
	v_mfma_f32_16x16x32_bf16 v[4:7], v[172:175], v[212:215], v[4:7]
	v_mfma_f32_16x16x32_bf16 v[0:3], v[180:183], v[212:215], v[0:3]
	v_mfma_f32_16x16x32_bf16 v[48:51], v[176:179], v[192:195], v[48:51]
	v_mfma_f32_16x16x32_bf16 v[40:43], v[184:187], v[192:195], v[40:43]
	v_mfma_f32_16x16x32_bf16 v[32:35], v[176:179], v[200:203], v[32:35]
	v_mfma_f32_16x16x32_bf16 v[24:27], v[184:187], v[200:203], v[24:27]
	v_mfma_f32_16x16x32_bf16 v[16:19], v[176:179], v[208:211], v[16:19]
	v_mfma_f32_16x16x32_bf16 v[8:11], v[184:187], v[208:211], v[8:11]
	v_mfma_f32_16x16x32_bf16 v[4:7], v[176:179], v[216:219], v[4:7]
	v_mfma_f32_16x16x32_bf16 v[0:3], v[184:187], v[216:219], v[0:3]
	s_setprio 0
	s_barrier
	s_add_i32 s64, s64, 2
	s_add_u32 s38, s38, 0x100
	s_addc_u32 s39, s39, 0
	s_add_u32 s62, s62, 0x100
	s_addc_u32 s63, s63, 0
	s_cmp_gt_u32 s64, 61
	s_cbranch_scc0 .LBB0_394
	s_and_b64 vcc, exec, s[12:13]
	s_cbranch_vccz .LBB0_397
	s_barrier

.LBB0_622:
	ds_read_b128 v[152:155], v149
	ds_read_b128 v[156:159], v149 offset:1024
	ds_read_b128 v[160:163], v149 offset:2048
	ds_read_b128 v[164:167], v149 offset:3072
	ds_read_b128 v[168:171], v150
	ds_read_b128 v[172:175], v150 offset:1024
	ds_read_b128 v[176:179], v150 offset:2048
	ds_read_b128 v[180:183], v150 offset:3072
	s_add_u32 s42, s40, 0xfff00080
	s_addc_u32 s43, s41, -1
	s_cmp_eq_u32 s61, 60
	s_cselect_b32 s45, s25, s43
	s_cselect_b32 s44, s57, s42
	s_cselect_b32 s43, s23, s60
	s_cselect_b32 s42, s58, s59
	v_lshl_add_u64 v[144:145], s[40:41], 0, v[136:137]
	s_add_i32 m0, s31, 0xc000
	ds_read_b128 v[184:187], v151
	ds_read_b128 v[188:191], v151 offset:1024
	ds_read_b128 v[192:195], v151 offset:2048
	ds_read_b128 v[196:199], v151 offset:3072
	ds_read_b128 v[200:203], v151 offset:4096
	ds_read_b128 v[204:207], v151 offset:5120
	ds_read_b128 v[208:211], v151 offset:6144
	ds_read_b128 v[212:215], v151 offset:7168
	global_load_lds_dwordx4 v[144:145], off
	v_lshl_add_u64 v[144:145], s[40:41], 0, v[138:139]
	s_add_i32 m0, s31, 0xe000
	s_nop 0
	global_load_lds_dwordx4 v[144:145], off
	s_waitcnt vmcnt(8)
	s_waitcnt lgkmcnt(0)
	s_barrier
	s_setprio 1
	v_mfma_f32_16x16x32_bf16 v[124:127], v[152:155], v[184:187], v[124:127]
	v_mfma_f32_16x16x32_bf16 v[120:123], v[160:163], v[184:187], v[120:123]
	v_mfma_f32_16x16x32_bf16 v[116:119], v[152:155], v[192:195], v[116:119]
	v_mfma_f32_16x16x32_bf16 v[108:111], v[160:163], v[192:195], v[108:111]
	v_mfma_f32_16x16x32_bf16 v[100:103], v[152:155], v[200:203], v[100:103]
	v_mfma_f32_16x16x32_bf16 v[92:95], v[160:163], v[200:203], v[92:95]
	v_mfma_f32_16x16x32_bf16 v[84:87], v[152:155], v[208:211], v[84:87]
	v_mfma_f32_16x16x32_bf16 v[76:79], v[160:163], v[208:211], v[76:79]
	v_mfma_f32_16x16x32_bf16 v[124:127], v[156:159], v[188:191], v[124:127]
	v_mfma_f32_16x16x32_bf16 v[120:123], v[164:167], v[188:191], v[120:123]
	v_mfma_f32_16x16x32_bf16 v[116:119], v[156:159], v[196:199], v[116:119]
	v_mfma_f32_16x16x32_bf16 v[108:111], v[164:167], v[196:199], v[108:111]
	v_mfma_f32_16x16x32_bf16 v[100:103], v[156:159], v[204:207], v[100:103]
	v_mfma_f32_16x16x32_bf16 v[92:95], v[164:167], v[204:207], v[92:95]
	v_mfma_f32_16x16x32_bf16 v[84:87], v[156:159], v[212:215], v[84:87]
	v_mfma_f32_16x16x32_bf16 v[76:79], v[164:167], v[212:215], v[76:79]
	v_mfma_f32_16x16x32_bf16 v[112:115], v[168:171], v[184:187], v[112:115]
	v_mfma_f32_16x16x32_bf16 v[104:107], v[176:179], v[184:187], v[104:107]
	v_mfma_f32_16x16x32_bf16 v[96:99], v[168:171], v[192:195], v[96:99]
	v_mfma_f32_16x16x32_bf16 v[88:91], v[176:179], v[192:195], v[88:91]
	v_mfma_f32_16x16x32_bf16 v[80:83], v[168:171], v[200:203], v[80:83]
	v_mfma_f32_16x16x32_bf16 v[72:75], v[176:179], v[200:203], v[72:75]
	v_mfma_f32_16x16x32_bf16 v[68:71], v[168:171], v[208:211], v[68:71]
	v_mfma_f32_16x16x32_bf16 v[64:67], v[176:179], v[208:211], v[64:67]
	v_mfma_f32_16x16x32_bf16 v[112:115], v[172:175], v[188:191], v[112:115]
	v_mfma_f32_16x16x32_bf16 v[104:107], v[180:183], v[188:191], v[104:107]
	v_mfma_f32_16x16x32_bf16 v[96:99], v[172:175], v[196:199], v[96:99]
	v_mfma_f32_16x16x32_bf16 v[88:91], v[180:183], v[196:199], v[88:91]
	v_mfma_f32_16x16x32_bf16 v[80:83], v[172:175], v[204:207], v[80:83]
	v_mfma_f32_16x16x32_bf16 v[72:75], v[180:183], v[204:207], v[72:75]
	v_mfma_f32_16x16x32_bf16 v[68:71], v[172:175], v[212:215], v[68:71]
	v_mfma_f32_16x16x32_bf16 v[64:67], v[180:183], v[212:215], v[64:67]
	s_setprio 0
	s_barrier
	s_add_i32 s62, s50, s29
	v_lshl_add_u64 v[144:145], s[42:43], 0, v[132:133]
	s_mov_b32 m0, s62
	ds_read_b128 v[184:187], v151 offset:16384
	ds_read_b128 v[188:191], v151 offset:17408
	ds_read_b128 v[192:195], v151 offset:18432
	ds_read_b128 v[196:199], v151 offset:19456
	ds_read_b128 v[200:203], v151 offset:20480
	ds_read_b128 v[204:207], v151 offset:21504
	ds_read_b128 v[208:211], v151 offset:22528
	ds_read_b128 v[212:215], v151 offset:23552
	global_load_lds_dwordx4 v[144:145], off
	s_add_i32 m0, s62, 0x2000
	s_add_u32 s62, s42, 0x100000
	v_lshl_add_u64 v[216:217], s[42:43], 0, v[128:129]
	s_addc_u32 s63, s43, 0
	s_add_i32 s64, s51, s29
	global_load_lds_dwordx4 v[216:217], off
	v_lshl_add_u64 v[218:219], s[62:63], 0, v[132:133]
	s_mov_b32 m0, s64
	v_lshl_add_u64 v[220:221], s[44:45], 0, v[130:131]
	global_load_lds_dwordx4 v[218:219], off
	v_lshl_add_u64 v[218:219], s[62:63], 0, v[128:129]
	s_add_i32 m0, s64, 0x2000
	s_nop 0
	global_load_lds_dwordx4 v[218:219], off
	v_lshl_add_u64 v[218:219], s[44:45], 0, v[134:135]
	s_mov_b32 m0, s31
	s_nop 0
	global_load_lds_dwordx4 v[218:219], off
	s_mov_b32 m0, s33
	s_nop 0
	global_load_lds_dwordx4 v[220:221], off
	s_waitcnt vmcnt(8)
	s_waitcnt lgkmcnt(0)
	s_barrier
	s_setprio 1
	v_mfma_f32_16x16x32_bf16 v[60:63], v[152:155], v[184:187], v[60:63]
	v_mfma_f32_16x16x32_bf16 v[56:59], v[160:163], v[184:187], v[56:59]
	v_mfma_f32_16x16x32_bf16 v[52:55], v[152:155], v[192:195], v[52:55]
	v_mfma_f32_16x16x32_bf16 v[44:47], v[160:163], v[192:195], v[44:47]
	v_mfma_f32_16x16x32_bf16 v[36:39], v[152:155], v[200:203], v[36:39]
	v_mfma_f32_16x16x32_bf16 v[28:31], v[160:163], v[200:203], v[28:31]
	v_mfma_f32_16x16x32_bf16 v[20:23], v[152:155], v[208:211], v[20:23]
	v_mfma_f32_16x16x32_bf16 v[12:15], v[160:163], v[208:211], v[12:15]
	v_mfma_f32_16x16x32_bf16 v[60:63], v[156:159], v[188:191], v[60:63]
	v_mfma_f32_16x16x32_bf16 v[56:59], v[164:167], v[188:191], v[56:59]
	v_mfma_f32_16x16x32_bf16 v[52:55], v[156:159], v[196:199], v[52:55]
	v_mfma_f32_16x16x32_bf16 v[44:47], v[164:167], v[196:199], v[44:47]
	v_mfma_f32_16x16x32_bf16 v[36:39], v[156:159], v[204:207], v[36:39]
	v_mfma_f32_16x16x32_bf16 v[28:31], v[164:167], v[204:207], v[28:31]
	v_mfma_f32_16x16x32_bf16 v[20:23], v[156:159], v[212:215], v[20:23]
	v_mfma_f32_16x16x32_bf16 v[12:15], v[164:167], v[212:215], v[12:15]
	v_mfma_f32_16x16x32_bf16 v[48:51], v[168:171], v[184:187], v[48:51]
	v_mfma_f32_16x16x32_bf16 v[40:43], v[176:179], v[184:187], v[40:43]
	v_mfma_f32_16x16x32_bf16 v[32:35], v[168:171], v[192:195], v[32:35]
	v_mfma_f32_16x16x32_bf16 v[24:27], v[176:179], v[192:195], v[24:27]
	v_mfma_f32_16x16x32_bf16 v[16:19], v[168:171], v[200:203], v[16:19]
	v_mfma_f32_16x16x32_bf16 v[8:11], v[176:179], v[200:203], v[8:11]
	v_mfma_f32_16x16x32_bf16 v[4:7], v[168:171], v[208:211], v[4:7]
	v_mfma_f32_16x16x32_bf16 v[0:3], v[176:179], v[208:211], v[0:3]
	v_mfma_f32_16x16x32_bf16 v[48:51], v[172:175], v[188:191], v[48:51]
	v_mfma_f32_16x16x32_bf16 v[40:43], v[180:183], v[188:191], v[40:43]
	v_mfma_f32_16x16x32_bf16 v[32:35], v[172:175], v[196:199], v[32:35]
	v_mfma_f32_16x16x32_bf16 v[24:27], v[180:183], v[196:199], v[24:27]
	v_mfma_f32_16x16x32_bf16 v[16:19], v[172:175], v[204:207], v[16:19]
	v_mfma_f32_16x16x32_bf16 v[8:11], v[180:183], v[204:207], v[8:11]
	v_mfma_f32_16x16x32_bf16 v[4:7], v[172:175], v[212:215], v[4:7]
	v_mfma_f32_16x16x32_bf16 v[0:3], v[180:183], v[212:215], v[0:3]
	s_setprio 0
	s_barrier
	s_add_i32 s62, 0, 0x18000
	s_add_i32 s63, 0, 0x1c000
	v_add_u32_e32 v164, s62, v147
	v_add_u32_e32 v180, s63, v147
	ds_read_b128 v[152:155], v164
	ds_read_b128 v[156:159], v164 offset:1024
	ds_read_b128 v[160:163], v164 offset:2048
	ds_read_b128 v[164:167], v164 offset:3072
	ds_read_b128 v[168:171], v180
	ds_read_b128 v[172:175], v180 offset:1024
	ds_read_b128 v[176:179], v180 offset:2048
	ds_read_b128 v[180:183], v180 offset:3072
	s_add_u32 s44, s44, 0x100000
	s_addc_u32 s45, s45, 0
	s_mov_b32 m0, s35
	v_lshl_add_u64 v[222:223], s[44:45], 0, v[134:135]
	ds_read_b128 v[184:187], v151 offset:32768
	ds_read_b128 v[188:191], v151 offset:33792
	ds_read_b128 v[192:195], v151 offset:34816
	ds_read_b128 v[196:199], v151 offset:35840
	ds_read_b128 v[200:203], v151 offset:36864
	ds_read_b128 v[204:207], v151 offset:37888
	ds_read_b128 v[208:211], v151 offset:38912
	ds_read_b128 v[212:215], v151 offset:39936
	global_load_lds_dwordx4 v[222:223], off
	v_lshl_add_u64 v[222:223], s[44:45], 0, v[130:131]
	s_mov_b32 m0, s39
	s_nop 0
	global_load_lds_dwordx4 v[222:223], off
	s_waitcnt vmcnt(8)
	s_waitcnt lgkmcnt(0)
	s_barrier
	s_setprio 1
	v_mfma_f32_16x16x32_bf16 v[124:127], v[152:155], v[184:187], v[124:127]
	v_mfma_f32_16x16x32_bf16 v[120:123], v[160:163], v[184:187], v[120:123]
	v_mfma_f32_16x16x32_bf16 v[116:119], v[152:155], v[192:195], v[116:119]
	v_mfma_f32_16x16x32_bf16 v[108:111], v[160:163], v[192:195], v[108:111]
	v_mfma_f32_16x16x32_bf16 v[100:103], v[152:155], v[200:203], v[100:103]
	v_mfma_f32_16x16x32_bf16 v[92:95], v[160:163], v[200:203], v[92:95]
	v_mfma_f32_16x16x32_bf16 v[84:87], v[152:155], v[208:211], v[84:87]
	v_mfma_f32_16x16x32_bf16 v[76:79], v[160:163], v[208:211], v[76:79]
	v_mfma_f32_16x16x32_bf16 v[124:127], v[156:159], v[188:191], v[124:127]
	v_mfma_f32_16x16x32_bf16 v[120:123], v[164:167], v[188:191], v[120:123]
	v_mfma_f32_16x16x32_bf16 v[116:119], v[156:159], v[196:199], v[116:119]
	v_mfma_f32_16x16x32_bf16 v[108:111], v[164:167], v[196:199], v[108:111]
	v_mfma_f32_16x16x32_bf16 v[100:103], v[156:159], v[204:207], v[100:103]
	v_mfma_f32_16x16x32_bf16 v[92:95], v[164:167], v[204:207], v[92:95]
	v_mfma_f32_16x16x32_bf16 v[84:87], v[156:159], v[212:215], v[84:87]
	v_mfma_f32_16x16x32_bf16 v[76:79], v[164:167], v[212:215], v[76:79]
	v_mfma_f32_16x16x32_bf16 v[112:115], v[168:171], v[184:187], v[112:115]
	v_mfma_f32_16x16x32_bf16 v[104:107], v[176:179], v[184:187], v[104:107]
	v_mfma_f32_16x16x32_bf16 v[96:99], v[168:171], v[192:195], v[96:99]
	v_mfma_f32_16x16x32_bf16 v[88:91], v[176:179], v[192:195], v[88:91]
	v_mfma_f32_16x16x32_bf16 v[80:83], v[168:171], v[200:203], v[80:83]
	v_mfma_f32_16x16x32_bf16 v[72:75], v[176:179], v[200:203], v[72:75]
	v_mfma_f32_16x16x32_bf16 v[68:71], v[168:171], v[208:211], v[68:71]
	v_mfma_f32_16x16x32_bf16 v[64:67], v[176:179], v[208:211], v[64:67]
	v_mfma_f32_16x16x32_bf16 v[112:115], v[172:175], v[188:191], v[112:115]
	v_mfma_f32_16x16x32_bf16 v[104:107], v[180:183], v[188:191], v[104:107]
	v_mfma_f32_16x16x32_bf16 v[96:99], v[172:175], v[196:199], v[96:99]
	v_mfma_f32_16x16x32_bf16 v[88:91], v[180:183], v[196:199], v[88:91]
	v_mfma_f32_16x16x32_bf16 v[80:83], v[172:175], v[204:207], v[80:83]
	v_mfma_f32_16x16x32_bf16 v[72:75], v[180:183], v[204:207], v[72:75]
	v_mfma_f32_16x16x32_bf16 v[68:71], v[172:175], v[212:215], v[68:71]
	v_mfma_f32_16x16x32_bf16 v[64:67], v[180:183], v[212:215], v[64:67]
	s_setprio 0
	s_barrier
	s_add_i32 s44, s62, s29
	v_lshl_add_u64 v[144:145], v[144:145], 0, s[8:9]
	s_mov_b32 m0, s44
	ds_read_b128 v[184:187], v151 offset:49152
	ds_read_b128 v[188:191], v151 offset:50176
	ds_read_b128 v[192:195], v151 offset:51200
	ds_read_b128 v[196:199], v151 offset:52224
	ds_read_b128 v[200:203], v151 offset:53248
	ds_read_b128 v[204:207], v151 offset:54272
	ds_read_b128 v[208:211], v151 offset:55296
	ds_read_b128 v[212:215], v151 offset:56320
	global_load_lds_dwordx4 v[144:145], off
	s_add_i32 m0, s44, 0x2000
	s_add_u32 s42, s42, 0x100080
	v_lshl_add_u64 v[144:145], v[216:217], 0, s[8:9]
	s_addc_u32 s43, s43, 0
	s_add_i32 s44, s63, s29
	global_load_lds_dwordx4 v[144:145], off
	v_lshl_add_u64 v[144:145], s[42:43], 0, v[132:133]
	s_mov_b32 m0, s44
	s_nop 0
	global_load_lds_dwordx4 v[144:145], off
	v_lshl_add_u64 v[144:145], s[42:43], 0, v[128:129]
	s_add_i32 m0, s44, 0x2000
	s_nop 0
	global_load_lds_dwordx4 v[144:145], off
	v_lshl_add_u64 v[144:145], v[218:219], 0, s[8:9]
	s_mov_b32 m0, s48
	s_nop 0
	global_load_lds_dwordx4 v[144:145], off
	v_lshl_add_u64 v[144:145], v[220:221], 0, s[8:9]
	s_mov_b32 m0, s49
	s_nop 0
	global_load_lds_dwordx4 v[144:145], off
	s_waitcnt vmcnt(8)
	s_waitcnt lgkmcnt(0)
	s_barrier
	s_setprio 1
	v_mfma_f32_16x16x32_bf16 v[60:63], v[152:155], v[184:187], v[60:63]
	v_mfma_f32_16x16x32_bf16 v[56:59], v[160:163], v[184:187], v[56:59]
	v_mfma_f32_16x16x32_bf16 v[52:55], v[152:155], v[192:195], v[52:55]
	v_mfma_f32_16x16x32_bf16 v[44:47], v[160:163], v[192:195], v[44:47]
	v_mfma_f32_16x16x32_bf16 v[36:39], v[152:155], v[200:203], v[36:39]
	v_mfma_f32_16x16x32_bf16 v[28:31], v[160:163], v[200:203], v[28:31]
	v_mfma_f32_16x16x32_bf16 v[20:23], v[152:155], v[208:211], v[20:23]
	v_mfma_f32_16x16x32_bf16 v[12:15], v[160:163], v[208:211], v[12:15]
	v_mfma_f32_16x16x32_bf16 v[60:63], v[156:159], v[188:191], v[60:63]
	v_mfma_f32_16x16x32_bf16 v[56:59], v[164:167], v[188:191], v[56:59]
	v_mfma_f32_16x16x32_bf16 v[52:55], v[156:159], v[196:199], v[52:55]
	v_mfma_f32_16x16x32_bf16 v[44:47], v[164:167], v[196:199], v[44:47]
	v_mfma_f32_16x16x32_bf16 v[36:39], v[156:159], v[204:207], v[36:39]
	v_mfma_f32_16x16x32_bf16 v[28:31], v[164:167], v[204:207], v[28:31]
	v_mfma_f32_16x16x32_bf16 v[20:23], v[156:159], v[212:215], v[20:23]
	v_mfma_f32_16x16x32_bf16 v[12:15], v[164:167], v[212:215], v[12:15]
	v_mfma_f32_16x16x32_bf16 v[48:51], v[168:171], v[184:187], v[48:51]
	v_mfma_f32_16x16x32_bf16 v[40:43], v[176:179], v[184:187], v[40:43]
	v_mfma_f32_16x16x32_bf16 v[32:35], v[168:171], v[192:195], v[32:35]
	v_mfma_f32_16x16x32_bf16 v[24:27], v[176:179], v[192:195], v[24:27]
	v_mfma_f32_16x16x32_bf16 v[16:19], v[168:171], v[200:203], v[16:19]
	v_mfma_f32_16x16x32_bf16 v[8:11], v[176:179], v[200:203], v[8:11]
	v_mfma_f32_16x16x32_bf16 v[4:7], v[168:171], v[208:211], v[4:7]
	v_mfma_f32_16x16x32_bf16 v[0:3], v[176:179], v[208:211], v[0:3]
	v_mfma_f32_16x16x32_bf16 v[48:51], v[172:175], v[188:191], v[48:51]
	v_mfma_f32_16x16x32_bf16 v[40:43], v[180:183], v[188:191], v[40:43]
	v_mfma_f32_16x16x32_bf16 v[32:35], v[172:175], v[196:199], v[32:35]
	v_mfma_f32_16x16x32_bf16 v[24:27], v[180:183], v[196:199], v[24:27]
	v_mfma_f32_16x16x32_bf16 v[16:19], v[172:175], v[204:207], v[16:19]
	v_mfma_f32_16x16x32_bf16 v[8:11], v[180:183], v[204:207], v[8:11]
	v_mfma_f32_16x16x32_bf16 v[4:7], v[172:175], v[212:215], v[4:7]
	v_mfma_f32_16x16x32_bf16 v[0:3], v[180:183], v[212:215], v[0:3]
	s_setprio 0
	s_barrier
	s_add_i32 s61, s61, 2
	s_add_u32 s40, s40, 0x100
	s_addc_u32 s41, s41, 0
	s_add_u32 s59, s59, 0x100
	s_addc_u32 s60, s60, 0
	s_cmp_gt_u32 s61, 61
	s_cbranch_scc0 .LBB0_622
	s_and_b64 vcc, exec, s[10:11]
	s_cbranch_vccz .LBB0_625
	s_barrier

.LBB0_773:
	ds_read_b128 v[144:147], v155
	ds_read_b128 v[148:151], v155 offset:1024
	ds_read_b128 v[158:161], v155 offset:2048
	ds_read_b128 v[162:165], v155 offset:3072
	ds_read_b128 v[166:169], v156
	ds_read_b128 v[170:173], v156 offset:1024
	ds_read_b128 v[174:177], v156 offset:2048
	ds_read_b128 v[178:181], v156 offset:3072
	s_add_u32 s36, s30, 0xfff80080
	s_addc_u32 s37, s31, -1
	s_cmp_eq_u32 s52, 28
	s_cselect_b32 s39, s23, s37
	s_cselect_b32 s38, s48, s36
	s_cselect_b32 s37, s21, s51
	s_cselect_b32 s36, s49, s50
	v_lshl_add_u64 v[214:215], s[30:31], 0, v[136:137]
	s_add_i32 m0, s17, 0xc000
	ds_read_b128 v[182:185], v157
	ds_read_b128 v[186:189], v157 offset:1024
	ds_read_b128 v[190:193], v157 offset:2048
	ds_read_b128 v[194:197], v157 offset:3072
	ds_read_b128 v[198:201], v157 offset:4096
	ds_read_b128 v[202:205], v157 offset:5120
	ds_read_b128 v[206:209], v157 offset:6144
	ds_read_b128 v[210:213], v157 offset:7168
	global_load_lds_dwordx4 v[214:215], off
	v_lshl_add_u64 v[214:215], s[30:31], 0, v[138:139]
	s_add_i32 m0, s17, 0xe000
	s_nop 0
	global_load_lds_dwordx4 v[214:215], off
	s_waitcnt vmcnt(8)
	s_waitcnt lgkmcnt(0)
	s_barrier
	s_setprio 1
	v_mfma_i32_16x16x64_i8 v[124:127], v[144:147], v[182:185], v[124:127]
	v_mfma_i32_16x16x64_i8 v[116:119], v[158:161], v[182:185], v[116:119]
	v_mfma_i32_16x16x64_i8 v[108:111], v[144:147], v[190:193], v[108:111]
	v_mfma_i32_16x16x64_i8 v[100:103], v[158:161], v[190:193], v[100:103]
	v_mfma_i32_16x16x64_i8 v[92:95], v[144:147], v[198:201], v[92:95]
	v_mfma_i32_16x16x64_i8 v[84:87], v[158:161], v[198:201], v[84:87]
	v_mfma_i32_16x16x64_i8 v[76:79], v[144:147], v[206:209], v[76:79]
	v_mfma_i32_16x16x64_i8 v[68:71], v[158:161], v[206:209], v[68:71]
	v_mfma_i32_16x16x64_i8 v[124:127], v[148:151], v[186:189], v[124:127]
	v_mfma_i32_16x16x64_i8 v[116:119], v[162:165], v[186:189], v[116:119]
	v_mfma_i32_16x16x64_i8 v[108:111], v[148:151], v[194:197], v[108:111]
	v_mfma_i32_16x16x64_i8 v[100:103], v[162:165], v[194:197], v[100:103]
	v_mfma_i32_16x16x64_i8 v[92:95], v[148:151], v[202:205], v[92:95]
	v_mfma_i32_16x16x64_i8 v[84:87], v[162:165], v[202:205], v[84:87]
	v_mfma_i32_16x16x64_i8 v[76:79], v[148:151], v[210:213], v[76:79]
	v_mfma_i32_16x16x64_i8 v[68:71], v[162:165], v[210:213], v[68:71]
	v_mfma_i32_16x16x64_i8 v[120:123], v[166:169], v[182:185], v[120:123]
	v_mfma_i32_16x16x64_i8 v[112:115], v[174:177], v[182:185], v[112:115]
	v_mfma_i32_16x16x64_i8 v[104:107], v[166:169], v[190:193], v[104:107]
	v_mfma_i32_16x16x64_i8 v[96:99], v[174:177], v[190:193], v[96:99]
	v_mfma_i32_16x16x64_i8 v[88:91], v[166:169], v[198:201], v[88:91]
	v_mfma_i32_16x16x64_i8 v[80:83], v[174:177], v[198:201], v[80:83]
	v_mfma_i32_16x16x64_i8 v[72:75], v[166:169], v[206:209], v[72:75]
	v_mfma_i32_16x16x64_i8 v[64:67], v[174:177], v[206:209], v[64:67]
	v_mfma_i32_16x16x64_i8 v[120:123], v[170:173], v[186:189], v[120:123]
	v_mfma_i32_16x16x64_i8 v[112:115], v[178:181], v[186:189], v[112:115]
	v_mfma_i32_16x16x64_i8 v[104:107], v[170:173], v[194:197], v[104:107]
	v_mfma_i32_16x16x64_i8 v[96:99], v[178:181], v[194:197], v[96:99]
	v_mfma_i32_16x16x64_i8 v[88:91], v[170:173], v[202:205], v[88:91]
	v_mfma_i32_16x16x64_i8 v[80:83], v[178:181], v[202:205], v[80:83]
	v_mfma_i32_16x16x64_i8 v[72:75], v[170:173], v[210:213], v[72:75]
	v_mfma_i32_16x16x64_i8 v[64:67], v[178:181], v[210:213], v[64:67]
	s_setprio 0
	s_barrier
	s_add_i32 s53, s44, s2
	v_lshl_add_u64 v[214:215], s[36:37], 0, v[132:133]
	s_mov_b32 m0, s53
	ds_read_b128 v[182:185], v157 offset:16384
	ds_read_b128 v[186:189], v157 offset:17408
	ds_read_b128 v[190:193], v157 offset:18432
	ds_read_b128 v[194:197], v157 offset:19456
	ds_read_b128 v[198:201], v157 offset:20480
	ds_read_b128 v[202:205], v157 offset:21504
	ds_read_b128 v[206:209], v157 offset:22528
	ds_read_b128 v[210:213], v157 offset:23552
	global_load_lds_dwordx4 v[214:215], off
	s_add_i32 m0, s53, 0x2000
	s_add_u32 s54, s36, 0x80000
	v_lshl_add_u64 v[216:217], s[36:37], 0, v[128:129]
	s_addc_u32 s55, s37, 0
	s_add_i32 s53, s45, s2
	global_load_lds_dwordx4 v[216:217], off
	v_lshl_add_u64 v[218:219], s[54:55], 0, v[132:133]
	s_mov_b32 m0, s53
	v_lshl_add_u64 v[220:221], s[38:39], 0, v[130:131]
	global_load_lds_dwordx4 v[218:219], off
	v_lshl_add_u64 v[218:219], s[54:55], 0, v[128:129]
	s_add_i32 m0, s53, 0x2000
	s_nop 0
	global_load_lds_dwordx4 v[218:219], off
	v_lshl_add_u64 v[218:219], s[38:39], 0, v[134:135]
	s_mov_b32 m0, s17
	s_nop 0
	global_load_lds_dwordx4 v[218:219], off
	s_mov_b32 m0, s29
	s_nop 0
	global_load_lds_dwordx4 v[220:221], off
	s_waitcnt vmcnt(8)
	s_waitcnt lgkmcnt(0)
	s_barrier
	s_setprio 1
	v_mfma_i32_16x16x64_i8 v[60:63], v[144:147], v[182:185], v[60:63]
	v_mfma_i32_16x16x64_i8 v[52:55], v[158:161], v[182:185], v[52:55]
	v_mfma_i32_16x16x64_i8 v[44:47], v[144:147], v[190:193], v[44:47]
	v_mfma_i32_16x16x64_i8 v[36:39], v[158:161], v[190:193], v[36:39]
	v_mfma_i32_16x16x64_i8 v[28:31], v[144:147], v[198:201], v[28:31]
	v_mfma_i32_16x16x64_i8 v[20:23], v[158:161], v[198:201], v[20:23]
	v_mfma_i32_16x16x64_i8 v[12:15], v[144:147], v[206:209], v[12:15]
	v_mfma_i32_16x16x64_i8 v[4:7], v[158:161], v[206:209], v[4:7]
	v_mfma_i32_16x16x64_i8 v[60:63], v[148:151], v[186:189], v[60:63]
	v_mfma_i32_16x16x64_i8 v[52:55], v[162:165], v[186:189], v[52:55]
	v_mfma_i32_16x16x64_i8 v[44:47], v[148:151], v[194:197], v[44:47]
	v_mfma_i32_16x16x64_i8 v[36:39], v[162:165], v[194:197], v[36:39]
	v_mfma_i32_16x16x64_i8 v[28:31], v[148:151], v[202:205], v[28:31]
	v_mfma_i32_16x16x64_i8 v[20:23], v[162:165], v[202:205], v[20:23]
	v_mfma_i32_16x16x64_i8 v[12:15], v[148:151], v[210:213], v[12:15]
	v_mfma_i32_16x16x64_i8 v[4:7], v[162:165], v[210:213], v[4:7]
	v_mfma_i32_16x16x64_i8 v[56:59], v[166:169], v[182:185], v[56:59]
	v_mfma_i32_16x16x64_i8 v[48:51], v[174:177], v[182:185], v[48:51]
	v_mfma_i32_16x16x64_i8 v[40:43], v[166:169], v[190:193], v[40:43]
	v_mfma_i32_16x16x64_i8 v[32:35], v[174:177], v[190:193], v[32:35]
	v_mfma_i32_16x16x64_i8 v[24:27], v[166:169], v[198:201], v[24:27]
	v_mfma_i32_16x16x64_i8 v[16:19], v[174:177], v[198:201], v[16:19]
	v_mfma_i32_16x16x64_i8 v[8:11], v[166:169], v[206:209], v[8:11]
	v_mfma_i32_16x16x64_i8 v[0:3], v[174:177], v[206:209], v[0:3]
	v_mfma_i32_16x16x64_i8 v[56:59], v[170:173], v[186:189], v[56:59]
	v_mfma_i32_16x16x64_i8 v[48:51], v[178:181], v[186:189], v[48:51]
	v_mfma_i32_16x16x64_i8 v[40:43], v[170:173], v[194:197], v[40:43]
	v_mfma_i32_16x16x64_i8 v[32:35], v[178:181], v[194:197], v[32:35]
	v_mfma_i32_16x16x64_i8 v[24:27], v[170:173], v[202:205], v[24:27]
	v_mfma_i32_16x16x64_i8 v[16:19], v[178:181], v[202:205], v[16:19]
	v_mfma_i32_16x16x64_i8 v[8:11], v[170:173], v[210:213], v[8:11]
	v_mfma_i32_16x16x64_i8 v[0:3], v[178:181], v[210:213], v[0:3]
	s_setprio 0
	s_barrier
	s_add_i32 s53, 0, 0x18000
	s_add_i32 s54, 0, 0x1c000
	v_add_u32_e32 v162, s53, v153
	v_add_u32_e32 v178, s54, v153
	ds_read_b128 v[144:147], v162
	ds_read_b128 v[148:151], v162 offset:1024
	ds_read_b128 v[158:161], v162 offset:2048
	ds_read_b128 v[162:165], v162 offset:3072
	ds_read_b128 v[166:169], v178
	ds_read_b128 v[170:173], v178 offset:1024
	ds_read_b128 v[174:177], v178 offset:2048
	ds_read_b128 v[178:181], v178 offset:3072
	s_add_u32 s38, s38, 0x80000
	s_addc_u32 s39, s39, 0
	s_mov_b32 m0, s33
	v_lshl_add_u64 v[222:223], s[38:39], 0, v[134:135]
	ds_read_b128 v[182:185], v157 offset:32768
	ds_read_b128 v[186:189], v157 offset:33792
	ds_read_b128 v[190:193], v157 offset:34816
	ds_read_b128 v[194:197], v157 offset:35840
	ds_read_b128 v[198:201], v157 offset:36864
	ds_read_b128 v[202:205], v157 offset:37888
	ds_read_b128 v[206:209], v157 offset:38912
	ds_read_b128 v[210:213], v157 offset:39936
	global_load_lds_dwordx4 v[222:223], off
	v_lshl_add_u64 v[222:223], s[38:39], 0, v[130:131]
	s_mov_b32 m0, s35
	s_nop 0
	global_load_lds_dwordx4 v[222:223], off
	s_waitcnt vmcnt(8)
	s_waitcnt lgkmcnt(0)
	s_barrier
	s_setprio 1
	v_mfma_i32_16x16x64_i8 v[124:127], v[144:147], v[182:185], v[124:127]
	v_mfma_i32_16x16x64_i8 v[116:119], v[158:161], v[182:185], v[116:119]
	v_mfma_i32_16x16x64_i8 v[108:111], v[144:147], v[190:193], v[108:111]
	v_mfma_i32_16x16x64_i8 v[100:103], v[158:161], v[190:193], v[100:103]
	v_mfma_i32_16x16x64_i8 v[92:95], v[144:147], v[198:201], v[92:95]
	v_mfma_i32_16x16x64_i8 v[84:87], v[158:161], v[198:201], v[84:87]
	v_mfma_i32_16x16x64_i8 v[76:79], v[144:147], v[206:209], v[76:79]
	v_mfma_i32_16x16x64_i8 v[68:71], v[158:161], v[206:209], v[68:71]
	v_mfma_i32_16x16x64_i8 v[124:127], v[148:151], v[186:189], v[124:127]
	v_mfma_i32_16x16x64_i8 v[116:119], v[162:165], v[186:189], v[116:119]
	v_mfma_i32_16x16x64_i8 v[108:111], v[148:151], v[194:197], v[108:111]
	v_mfma_i32_16x16x64_i8 v[100:103], v[162:165], v[194:197], v[100:103]
	v_mfma_i32_16x16x64_i8 v[92:95], v[148:151], v[202:205], v[92:95]
	v_mfma_i32_16x16x64_i8 v[84:87], v[162:165], v[202:205], v[84:87]
	v_mfma_i32_16x16x64_i8 v[76:79], v[148:151], v[210:213], v[76:79]
	v_mfma_i32_16x16x64_i8 v[68:71], v[162:165], v[210:213], v[68:71]
	v_mfma_i32_16x16x64_i8 v[120:123], v[166:169], v[182:185], v[120:123]
	v_mfma_i32_16x16x64_i8 v[112:115], v[174:177], v[182:185], v[112:115]
	v_mfma_i32_16x16x64_i8 v[104:107], v[166:169], v[190:193], v[104:107]
	v_mfma_i32_16x16x64_i8 v[96:99], v[174:177], v[190:193], v[96:99]
	v_mfma_i32_16x16x64_i8 v[88:91], v[166:169], v[198:201], v[88:91]
	v_mfma_i32_16x16x64_i8 v[80:83], v[174:177], v[198:201], v[80:83]
	v_mfma_i32_16x16x64_i8 v[72:75], v[166:169], v[206:209], v[72:75]
	v_mfma_i32_16x16x64_i8 v[64:67], v[174:177], v[206:209], v[64:67]
	v_mfma_i32_16x16x64_i8 v[120:123], v[170:173], v[186:189], v[120:123]
	v_mfma_i32_16x16x64_i8 v[112:115], v[178:181], v[186:189], v[112:115]
	v_mfma_i32_16x16x64_i8 v[104:107], v[170:173], v[194:197], v[104:107]
	v_mfma_i32_16x16x64_i8 v[96:99], v[178:181], v[194:197], v[96:99]
	v_mfma_i32_16x16x64_i8 v[88:91], v[170:173], v[202:205], v[88:91]
	v_mfma_i32_16x16x64_i8 v[80:83], v[178:181], v[202:205], v[80:83]
	v_mfma_i32_16x16x64_i8 v[72:75], v[170:173], v[210:213], v[72:75]
	v_mfma_i32_16x16x64_i8 v[64:67], v[178:181], v[210:213], v[64:67]
	s_setprio 0
	s_barrier
	s_add_i32 s38, s53, s2
	v_lshl_add_u64 v[214:215], v[214:215], 0, s[12:13]
	s_mov_b32 m0, s38
	ds_read_b128 v[182:185], v157 offset:49152
	ds_read_b128 v[186:189], v157 offset:50176
	ds_read_b128 v[190:193], v157 offset:51200
	ds_read_b128 v[194:197], v157 offset:52224
	ds_read_b128 v[198:201], v157 offset:53248
	ds_read_b128 v[202:205], v157 offset:54272
	ds_read_b128 v[206:209], v157 offset:55296
	ds_read_b128 v[210:213], v157 offset:56320
	global_load_lds_dwordx4 v[214:215], off
	s_add_i32 m0, s38, 0x2000
	s_add_u32 s36, s36, 0x80080
	v_lshl_add_u64 v[214:215], v[216:217], 0, s[12:13]
	s_addc_u32 s37, s37, 0
	s_add_i32 s38, s54, s2
	global_load_lds_dwordx4 v[214:215], off
	v_lshl_add_u64 v[214:215], s[36:37], 0, v[132:133]
	s_mov_b32 m0, s38
	s_nop 0
	global_load_lds_dwordx4 v[214:215], off
	v_lshl_add_u64 v[214:215], s[36:37], 0, v[128:129]
	s_add_i32 m0, s38, 0x2000
	s_nop 0
	global_load_lds_dwordx4 v[214:215], off
	v_lshl_add_u64 v[214:215], v[218:219], 0, s[12:13]
	s_mov_b32 m0, s42
	s_nop 0
	global_load_lds_dwordx4 v[214:215], off
	v_lshl_add_u64 v[214:215], v[220:221], 0, s[12:13]
	s_mov_b32 m0, s43
	s_nop 0
	global_load_lds_dwordx4 v[214:215], off
	s_waitcnt vmcnt(8)
	s_waitcnt lgkmcnt(0)
	s_barrier
	s_setprio 1
	v_mfma_i32_16x16x64_i8 v[60:63], v[144:147], v[182:185], v[60:63]
	v_mfma_i32_16x16x64_i8 v[52:55], v[158:161], v[182:185], v[52:55]
	v_mfma_i32_16x16x64_i8 v[44:47], v[144:147], v[190:193], v[44:47]
	v_mfma_i32_16x16x64_i8 v[36:39], v[158:161], v[190:193], v[36:39]
	v_mfma_i32_16x16x64_i8 v[28:31], v[144:147], v[198:201], v[28:31]
	v_mfma_i32_16x16x64_i8 v[20:23], v[158:161], v[198:201], v[20:23]
	v_mfma_i32_16x16x64_i8 v[12:15], v[144:147], v[206:209], v[12:15]
	v_mfma_i32_16x16x64_i8 v[4:7], v[158:161], v[206:209], v[4:7]
	v_mfma_i32_16x16x64_i8 v[60:63], v[148:151], v[186:189], v[60:63]
	v_mfma_i32_16x16x64_i8 v[52:55], v[162:165], v[186:189], v[52:55]
	v_mfma_i32_16x16x64_i8 v[44:47], v[148:151], v[194:197], v[44:47]
	v_mfma_i32_16x16x64_i8 v[36:39], v[162:165], v[194:197], v[36:39]
	v_mfma_i32_16x16x64_i8 v[28:31], v[148:151], v[202:205], v[28:31]
	v_mfma_i32_16x16x64_i8 v[20:23], v[162:165], v[202:205], v[20:23]
	v_mfma_i32_16x16x64_i8 v[12:15], v[148:151], v[210:213], v[12:15]
	v_mfma_i32_16x16x64_i8 v[4:7], v[162:165], v[210:213], v[4:7]
	v_mfma_i32_16x16x64_i8 v[56:59], v[166:169], v[182:185], v[56:59]
	v_mfma_i32_16x16x64_i8 v[48:51], v[174:177], v[182:185], v[48:51]
	v_mfma_i32_16x16x64_i8 v[40:43], v[166:169], v[190:193], v[40:43]
	v_mfma_i32_16x16x64_i8 v[32:35], v[174:177], v[190:193], v[32:35]
	v_mfma_i32_16x16x64_i8 v[24:27], v[166:169], v[198:201], v[24:27]
	v_mfma_i32_16x16x64_i8 v[16:19], v[174:177], v[198:201], v[16:19]
	v_mfma_i32_16x16x64_i8 v[8:11], v[166:169], v[206:209], v[8:11]
	v_mfma_i32_16x16x64_i8 v[0:3], v[174:177], v[206:209], v[0:3]
	v_mfma_i32_16x16x64_i8 v[56:59], v[170:173], v[186:189], v[56:59]
	v_mfma_i32_16x16x64_i8 v[48:51], v[178:181], v[186:189], v[48:51]
	v_mfma_i32_16x16x64_i8 v[40:43], v[170:173], v[194:197], v[40:43]
	v_mfma_i32_16x16x64_i8 v[32:35], v[178:181], v[194:197], v[32:35]
	v_mfma_i32_16x16x64_i8 v[24:27], v[170:173], v[202:205], v[24:27]
	v_mfma_i32_16x16x64_i8 v[16:19], v[178:181], v[202:205], v[16:19]
	v_mfma_i32_16x16x64_i8 v[8:11], v[170:173], v[210:213], v[8:11]
	v_mfma_i32_16x16x64_i8 v[0:3], v[178:181], v[210:213], v[0:3]
	s_setprio 0
	s_barrier
	s_add_i32 s52, s52, 2
	s_add_u32 s30, s30, 0x100
	s_addc_u32 s31, s31, 0
	s_add_u32 s50, s50, 0x100
	s_addc_u32 s51, s51, 0
	s_cmp_gt_u32 s52, 29
	s_cbranch_scc0 .LBB0_773
	s_and_b64 vcc, exec, s[14:15]
	s_cbranch_vccz .LBB0_776
	s_barrier

.LBB0_858:
	ds_read_b128 v[152:155], v149
	ds_read_b128 v[156:159], v149 offset:1024
	ds_read_b128 v[160:163], v149 offset:2048
	ds_read_b128 v[164:167], v149 offset:3072
	ds_read_b128 v[168:171], v150
	ds_read_b128 v[172:175], v150 offset:1024
	ds_read_b128 v[176:179], v150 offset:2048
	ds_read_b128 v[180:183], v150 offset:3072
	s_add_u32 s26, s24, 0x100
	s_addc_u32 s27, s25, 0
	s_cmpk_eq_i32 s54, 0xa8
	s_cselect_b32 s31, s5, s27
	s_cselect_b32 s30, s4, s26
	s_cselect_b32 s29, s23, s53
	s_cselect_b32 s28, s22, s52
	v_lshl_add_u64 v[144:145], s[24:25], 0, v[136:137]
	s_add_i32 m0, s33, 0xc000
	ds_read_b128 v[184:187], v151
	ds_read_b128 v[188:191], v151 offset:1024
	ds_read_b128 v[192:195], v151 offset:2048
	ds_read_b128 v[196:199], v151 offset:3072
	ds_read_b128 v[200:203], v151 offset:4096
	ds_read_b128 v[204:207], v151 offset:5120
	ds_read_b128 v[208:211], v151 offset:6144
	ds_read_b128 v[212:215], v151 offset:7168
	global_load_lds_dwordx4 v[144:145], off
	v_lshl_add_u64 v[144:145], s[24:25], 0, v[138:139]
	s_add_i32 m0, s33, 0xe000
	s_nop 0
	global_load_lds_dwordx4 v[144:145], off
	s_waitcnt vmcnt(8)
	s_waitcnt lgkmcnt(0)
	s_barrier
	s_setprio 1
	v_mfma_f32_16x16x32_bf16 v[124:127], v[152:155], v[184:187], v[124:127]
	v_mfma_f32_16x16x32_bf16 v[120:123], v[160:163], v[184:187], v[120:123]
	v_mfma_f32_16x16x32_bf16 v[116:119], v[152:155], v[192:195], v[116:119]
	v_mfma_f32_16x16x32_bf16 v[108:111], v[160:163], v[192:195], v[108:111]
	v_mfma_f32_16x16x32_bf16 v[100:103], v[152:155], v[200:203], v[100:103]
	v_mfma_f32_16x16x32_bf16 v[92:95], v[160:163], v[200:203], v[92:95]
	v_mfma_f32_16x16x32_bf16 v[84:87], v[152:155], v[208:211], v[84:87]
	v_mfma_f32_16x16x32_bf16 v[76:79], v[160:163], v[208:211], v[76:79]
	v_mfma_f32_16x16x32_bf16 v[124:127], v[156:159], v[188:191], v[124:127]
	v_mfma_f32_16x16x32_bf16 v[120:123], v[164:167], v[188:191], v[120:123]
	v_mfma_f32_16x16x32_bf16 v[116:119], v[156:159], v[196:199], v[116:119]
	v_mfma_f32_16x16x32_bf16 v[108:111], v[164:167], v[196:199], v[108:111]
	v_mfma_f32_16x16x32_bf16 v[100:103], v[156:159], v[204:207], v[100:103]
	v_mfma_f32_16x16x32_bf16 v[92:95], v[164:167], v[204:207], v[92:95]
	v_mfma_f32_16x16x32_bf16 v[84:87], v[156:159], v[212:215], v[84:87]
	v_mfma_f32_16x16x32_bf16 v[76:79], v[164:167], v[212:215], v[76:79]
	v_mfma_f32_16x16x32_bf16 v[112:115], v[168:171], v[184:187], v[112:115]
	v_mfma_f32_16x16x32_bf16 v[104:107], v[176:179], v[184:187], v[104:107]
	v_mfma_f32_16x16x32_bf16 v[96:99], v[168:171], v[192:195], v[96:99]
	v_mfma_f32_16x16x32_bf16 v[88:91], v[176:179], v[192:195], v[88:91]
	v_mfma_f32_16x16x32_bf16 v[80:83], v[168:171], v[200:203], v[80:83]
	v_mfma_f32_16x16x32_bf16 v[72:75], v[176:179], v[200:203], v[72:75]
	v_mfma_f32_16x16x32_bf16 v[68:71], v[168:171], v[208:211], v[68:71]
	v_mfma_f32_16x16x32_bf16 v[64:67], v[176:179], v[208:211], v[64:67]
	v_mfma_f32_16x16x32_bf16 v[112:115], v[172:175], v[188:191], v[112:115]
	v_mfma_f32_16x16x32_bf16 v[104:107], v[180:183], v[188:191], v[104:107]
	v_mfma_f32_16x16x32_bf16 v[96:99], v[172:175], v[196:199], v[96:99]
	v_mfma_f32_16x16x32_bf16 v[88:91], v[180:183], v[196:199], v[88:91]
	v_mfma_f32_16x16x32_bf16 v[80:83], v[172:175], v[204:207], v[80:83]
	v_mfma_f32_16x16x32_bf16 v[72:75], v[180:183], v[204:207], v[72:75]
	v_mfma_f32_16x16x32_bf16 v[68:71], v[172:175], v[212:215], v[68:71]
	v_mfma_f32_16x16x32_bf16 v[64:67], v[180:183], v[212:215], v[64:67]
	s_setprio 0
	s_barrier
	s_add_i32 s24, s42, s2
	v_lshl_add_u64 v[144:145], s[28:29], 0, v[132:133]
	s_mov_b32 m0, s24
	ds_read_b128 v[184:187], v151 offset:16384
	ds_read_b128 v[188:191], v151 offset:17408
	ds_read_b128 v[192:195], v151 offset:18432
	ds_read_b128 v[196:199], v151 offset:19456
	ds_read_b128 v[200:203], v151 offset:20480
	ds_read_b128 v[204:207], v151 offset:21504
	ds_read_b128 v[208:211], v151 offset:22528
	ds_read_b128 v[212:215], v151 offset:23552
	global_load_lds_dwordx4 v[144:145], off
	s_add_i32 m0, s24, 0x2000
	s_add_u32 s24, s28, 0x2b0000
	v_lshl_add_u64 v[216:217], s[28:29], 0, v[128:129]
	s_addc_u32 s25, s29, 0
	s_add_i32 s55, s43, s2
	global_load_lds_dwordx4 v[216:217], off
	v_lshl_add_u64 v[218:219], s[24:25], 0, v[132:133]
	s_mov_b32 m0, s55
	v_lshl_add_u64 v[220:221], s[30:31], 0, v[130:131]
	global_load_lds_dwordx4 v[218:219], off
	v_lshl_add_u64 v[218:219], s[24:25], 0, v[128:129]
	s_add_i32 m0, s55, 0x2000
	s_nop 0
	global_load_lds_dwordx4 v[218:219], off
	v_lshl_add_u64 v[218:219], s[30:31], 0, v[134:135]
	s_mov_b32 m0, s33
	s_nop 0
	global_load_lds_dwordx4 v[218:219], off
	s_mov_b32 m0, s35
	s_nop 0
	global_load_lds_dwordx4 v[220:221], off
	s_waitcnt vmcnt(8)
	s_waitcnt lgkmcnt(0)
	s_barrier
	s_setprio 1
	v_mfma_f32_16x16x32_bf16 v[60:63], v[152:155], v[184:187], v[60:63]
	v_mfma_f32_16x16x32_bf16 v[56:59], v[160:163], v[184:187], v[56:59]
	v_mfma_f32_16x16x32_bf16 v[52:55], v[152:155], v[192:195], v[52:55]
	v_mfma_f32_16x16x32_bf16 v[44:47], v[160:163], v[192:195], v[44:47]
	v_mfma_f32_16x16x32_bf16 v[36:39], v[152:155], v[200:203], v[36:39]
	v_mfma_f32_16x16x32_bf16 v[28:31], v[160:163], v[200:203], v[28:31]
	v_mfma_f32_16x16x32_bf16 v[20:23], v[152:155], v[208:211], v[20:23]
	v_mfma_f32_16x16x32_bf16 v[12:15], v[160:163], v[208:211], v[12:15]
	v_mfma_f32_16x16x32_bf16 v[60:63], v[156:159], v[188:191], v[60:63]
	v_mfma_f32_16x16x32_bf16 v[56:59], v[164:167], v[188:191], v[56:59]
	v_mfma_f32_16x16x32_bf16 v[52:55], v[156:159], v[196:199], v[52:55]
	v_mfma_f32_16x16x32_bf16 v[44:47], v[164:167], v[196:199], v[44:47]
	v_mfma_f32_16x16x32_bf16 v[36:39], v[156:159], v[204:207], v[36:39]
	v_mfma_f32_16x16x32_bf16 v[28:31], v[164:167], v[204:207], v[28:31]
	v_mfma_f32_16x16x32_bf16 v[20:23], v[156:159], v[212:215], v[20:23]
	v_mfma_f32_16x16x32_bf16 v[12:15], v[164:167], v[212:215], v[12:15]
	v_mfma_f32_16x16x32_bf16 v[48:51], v[168:171], v[184:187], v[48:51]
	v_mfma_f32_16x16x32_bf16 v[40:43], v[176:179], v[184:187], v[40:43]
	v_mfma_f32_16x16x32_bf16 v[32:35], v[168:171], v[192:195], v[32:35]
	v_mfma_f32_16x16x32_bf16 v[24:27], v[176:179], v[192:195], v[24:27]
	v_mfma_f32_16x16x32_bf16 v[16:19], v[168:171], v[200:203], v[16:19]
	v_mfma_f32_16x16x32_bf16 v[8:11], v[176:179], v[200:203], v[8:11]
	v_mfma_f32_16x16x32_bf16 v[4:7], v[168:171], v[208:211], v[4:7]
	v_mfma_f32_16x16x32_bf16 v[0:3], v[176:179], v[208:211], v[0:3]
	v_mfma_f32_16x16x32_bf16 v[48:51], v[172:175], v[188:191], v[48:51]
	v_mfma_f32_16x16x32_bf16 v[40:43], v[180:183], v[188:191], v[40:43]
	v_mfma_f32_16x16x32_bf16 v[32:35], v[172:175], v[196:199], v[32:35]
	v_mfma_f32_16x16x32_bf16 v[24:27], v[180:183], v[196:199], v[24:27]
	v_mfma_f32_16x16x32_bf16 v[16:19], v[172:175], v[204:207], v[16:19]
	v_mfma_f32_16x16x32_bf16 v[8:11], v[180:183], v[204:207], v[8:11]
	v_mfma_f32_16x16x32_bf16 v[4:7], v[172:175], v[212:215], v[4:7]
	v_mfma_f32_16x16x32_bf16 v[0:3], v[180:183], v[212:215], v[0:3]
	s_setprio 0
	s_barrier
	s_add_i32 s55, 0, 0x18000
	s_add_i32 s58, 0, 0x1c000
	v_add_u32_e32 v164, s55, v147
	v_add_u32_e32 v180, s58, v147
	ds_read_b128 v[152:155], v164
	ds_read_b128 v[156:159], v164 offset:1024
	ds_read_b128 v[160:163], v164 offset:2048
	ds_read_b128 v[164:167], v164 offset:3072
	ds_read_b128 v[168:171], v180
	ds_read_b128 v[172:175], v180 offset:1024
	ds_read_b128 v[176:179], v180 offset:2048
	ds_read_b128 v[180:183], v180 offset:3072
	s_add_u32 s24, s30, 0x2b0000
	s_addc_u32 s25, s31, 0
	s_mov_b32 m0, s36
	v_lshl_add_u64 v[222:223], s[24:25], 0, v[134:135]
	ds_read_b128 v[184:187], v151 offset:32768
	ds_read_b128 v[188:191], v151 offset:33792
	ds_read_b128 v[192:195], v151 offset:34816
	ds_read_b128 v[196:199], v151 offset:35840
	ds_read_b128 v[200:203], v151 offset:36864
	ds_read_b128 v[204:207], v151 offset:37888
	ds_read_b128 v[208:211], v151 offset:38912
	ds_read_b128 v[212:215], v151 offset:39936
	global_load_lds_dwordx4 v[222:223], off
	v_lshl_add_u64 v[222:223], s[24:25], 0, v[130:131]
	s_mov_b32 m0, s37
	s_nop 0
	global_load_lds_dwordx4 v[222:223], off
	s_waitcnt vmcnt(8)
	s_waitcnt lgkmcnt(0)
	s_barrier
	s_setprio 1
	v_mfma_f32_16x16x32_bf16 v[124:127], v[152:155], v[184:187], v[124:127]
	v_mfma_f32_16x16x32_bf16 v[120:123], v[160:163], v[184:187], v[120:123]
	v_mfma_f32_16x16x32_bf16 v[116:119], v[152:155], v[192:195], v[116:119]
	v_mfma_f32_16x16x32_bf16 v[108:111], v[160:163], v[192:195], v[108:111]
	v_mfma_f32_16x16x32_bf16 v[100:103], v[152:155], v[200:203], v[100:103]
	v_mfma_f32_16x16x32_bf16 v[92:95], v[160:163], v[200:203], v[92:95]
	v_mfma_f32_16x16x32_bf16 v[84:87], v[152:155], v[208:211], v[84:87]
	v_mfma_f32_16x16x32_bf16 v[76:79], v[160:163], v[208:211], v[76:79]
	v_mfma_f32_16x16x32_bf16 v[124:127], v[156:159], v[188:191], v[124:127]
	v_mfma_f32_16x16x32_bf16 v[120:123], v[164:167], v[188:191], v[120:123]
	v_mfma_f32_16x16x32_bf16 v[116:119], v[156:159], v[196:199], v[116:119]
	v_mfma_f32_16x16x32_bf16 v[108:111], v[164:167], v[196:199], v[108:111]
	v_mfma_f32_16x16x32_bf16 v[100:103], v[156:159], v[204:207], v[100:103]
	v_mfma_f32_16x16x32_bf16 v[92:95], v[164:167], v[204:207], v[92:95]
	v_mfma_f32_16x16x32_bf16 v[84:87], v[156:159], v[212:215], v[84:87]
	v_mfma_f32_16x16x32_bf16 v[76:79], v[164:167], v[212:215], v[76:79]
	v_mfma_f32_16x16x32_bf16 v[112:115], v[168:171], v[184:187], v[112:115]
	v_mfma_f32_16x16x32_bf16 v[104:107], v[176:179], v[184:187], v[104:107]
	v_mfma_f32_16x16x32_bf16 v[96:99], v[168:171], v[192:195], v[96:99]
	v_mfma_f32_16x16x32_bf16 v[88:91], v[176:179], v[192:195], v[88:91]
	v_mfma_f32_16x16x32_bf16 v[80:83], v[168:171], v[200:203], v[80:83]
	v_mfma_f32_16x16x32_bf16 v[72:75], v[176:179], v[200:203], v[72:75]
	v_mfma_f32_16x16x32_bf16 v[68:71], v[168:171], v[208:211], v[68:71]
	v_mfma_f32_16x16x32_bf16 v[64:67], v[176:179], v[208:211], v[64:67]
	v_mfma_f32_16x16x32_bf16 v[112:115], v[172:175], v[188:191], v[112:115]
	v_mfma_f32_16x16x32_bf16 v[104:107], v[180:183], v[188:191], v[104:107]
	v_mfma_f32_16x16x32_bf16 v[96:99], v[172:175], v[196:199], v[96:99]
	v_mfma_f32_16x16x32_bf16 v[88:91], v[180:183], v[196:199], v[88:91]
	v_mfma_f32_16x16x32_bf16 v[80:83], v[172:175], v[204:207], v[80:83]
	v_mfma_f32_16x16x32_bf16 v[72:75], v[180:183], v[204:207], v[72:75]
	v_mfma_f32_16x16x32_bf16 v[68:71], v[172:175], v[212:215], v[68:71]
	v_mfma_f32_16x16x32_bf16 v[64:67], v[180:183], v[212:215], v[64:67]
	s_setprio 0
	s_barrier
	s_add_i32 s24, s55, s2
	v_lshl_add_u64 v[144:145], v[144:145], 0, s[8:9]
	s_mov_b32 m0, s24
	ds_read_b128 v[184:187], v151 offset:49152
	ds_read_b128 v[188:191], v151 offset:50176
	ds_read_b128 v[192:195], v151 offset:51200
	ds_read_b128 v[196:199], v151 offset:52224
	ds_read_b128 v[200:203], v151 offset:53248
	ds_read_b128 v[204:207], v151 offset:54272
	ds_read_b128 v[208:211], v151 offset:55296
	ds_read_b128 v[212:215], v151 offset:56320
	global_load_lds_dwordx4 v[144:145], off
	s_add_i32 m0, s24, 0x2000
	s_add_u32 s24, s28, 0x2b0080
	v_lshl_add_u64 v[144:145], v[216:217], 0, s[8:9]
	s_addc_u32 s25, s29, 0
	s_add_i32 s28, s58, s2
	global_load_lds_dwordx4 v[144:145], off
	v_lshl_add_u64 v[144:145], s[24:25], 0, v[132:133]
	s_mov_b32 m0, s28
	s_nop 0
	global_load_lds_dwordx4 v[144:145], off
	v_lshl_add_u64 v[144:145], s[24:25], 0, v[128:129]
	s_add_i32 m0, s28, 0x2000
	s_nop 0
	global_load_lds_dwordx4 v[144:145], off
	v_lshl_add_u64 v[144:145], v[218:219], 0, s[8:9]
	s_mov_b32 m0, s40
	s_nop 0
	global_load_lds_dwordx4 v[144:145], off
	v_lshl_add_u64 v[144:145], v[220:221], 0, s[8:9]
	s_mov_b32 m0, s41
	s_nop 0
	global_load_lds_dwordx4 v[144:145], off
	s_waitcnt vmcnt(8)
	s_waitcnt lgkmcnt(0)
	s_barrier
	s_setprio 1
	v_mfma_f32_16x16x32_bf16 v[60:63], v[152:155], v[184:187], v[60:63]
	v_mfma_f32_16x16x32_bf16 v[56:59], v[160:163], v[184:187], v[56:59]
	v_mfma_f32_16x16x32_bf16 v[52:55], v[152:155], v[192:195], v[52:55]
	v_mfma_f32_16x16x32_bf16 v[44:47], v[160:163], v[192:195], v[44:47]
	v_mfma_f32_16x16x32_bf16 v[36:39], v[152:155], v[200:203], v[36:39]
	v_mfma_f32_16x16x32_bf16 v[28:31], v[160:163], v[200:203], v[28:31]
	v_mfma_f32_16x16x32_bf16 v[20:23], v[152:155], v[208:211], v[20:23]
	v_mfma_f32_16x16x32_bf16 v[12:15], v[160:163], v[208:211], v[12:15]
	v_mfma_f32_16x16x32_bf16 v[60:63], v[156:159], v[188:191], v[60:63]
	v_mfma_f32_16x16x32_bf16 v[56:59], v[164:167], v[188:191], v[56:59]
	v_mfma_f32_16x16x32_bf16 v[52:55], v[156:159], v[196:199], v[52:55]
	v_mfma_f32_16x16x32_bf16 v[44:47], v[164:167], v[196:199], v[44:47]
	v_mfma_f32_16x16x32_bf16 v[36:39], v[156:159], v[204:207], v[36:39]
	v_mfma_f32_16x16x32_bf16 v[28:31], v[164:167], v[204:207], v[28:31]
	v_mfma_f32_16x16x32_bf16 v[20:23], v[156:159], v[212:215], v[20:23]
	v_mfma_f32_16x16x32_bf16 v[12:15], v[164:167], v[212:215], v[12:15]
	v_mfma_f32_16x16x32_bf16 v[48:51], v[168:171], v[184:187], v[48:51]
	v_mfma_f32_16x16x32_bf16 v[40:43], v[176:179], v[184:187], v[40:43]
	v_mfma_f32_16x16x32_bf16 v[32:35], v[168:171], v[192:195], v[32:35]
	v_mfma_f32_16x16x32_bf16 v[24:27], v[176:179], v[192:195], v[24:27]
	v_mfma_f32_16x16x32_bf16 v[16:19], v[168:171], v[200:203], v[16:19]
	v_mfma_f32_16x16x32_bf16 v[8:11], v[176:179], v[200:203], v[8:11]
	v_mfma_f32_16x16x32_bf16 v[4:7], v[168:171], v[208:211], v[4:7]
	v_mfma_f32_16x16x32_bf16 v[0:3], v[176:179], v[208:211], v[0:3]
	v_mfma_f32_16x16x32_bf16 v[48:51], v[172:175], v[188:191], v[48:51]
	v_mfma_f32_16x16x32_bf16 v[40:43], v[180:183], v[188:191], v[40:43]
	v_mfma_f32_16x16x32_bf16 v[32:35], v[172:175], v[196:199], v[32:35]
	v_mfma_f32_16x16x32_bf16 v[24:27], v[180:183], v[196:199], v[24:27]
	v_mfma_f32_16x16x32_bf16 v[16:19], v[172:175], v[204:207], v[16:19]
	v_mfma_f32_16x16x32_bf16 v[8:11], v[180:183], v[204:207], v[8:11]
	v_mfma_f32_16x16x32_bf16 v[4:7], v[172:175], v[212:215], v[4:7]
	v_mfma_f32_16x16x32_bf16 v[0:3], v[180:183], v[212:215], v[0:3]
	s_setprio 0
	s_barrier
	s_add_i32 s54, s54, 2
	s_add_u32 s52, s52, 0x100
	s_addc_u32 s53, s53, 0
	s_cmpk_gt_u32 s54, 0xa9
	s_mov_b64 s[24:25], s[26:27]
	s_cbranch_scc0 .LBB0_858
	s_and_b64 vcc, exec, s[10:11]
	s_cbranch_vccz .LBB0_861
	s_barrier
